# F q-tile bf16 pack via v_cvt_pk_bf16_f32 (in place per accumulator quad) instead of the integer RNE bit trick
# speedup vs baseline: 1.0317x; 1.0045x over previous
.LBB0_865:
	v_mov_b32_e32 v128, v176
	s_waitcnt vmcnt(0)
	s_barrier
	v_mov_b32_e32 v137, v176
	v_and_b32_e32 v130, 15, v128
	v_lshrrev_b32_e32 v131, 1, v128
	v_and_or_b32 v130, v131, s81, v130
	v_ashrrev_i32_e32 v131, 2, v128
	v_lshrrev_b32_e32 v128, 2, v128
	v_and_b32_e32 v128, 12, v128
	v_and_or_b32 v128, v131, s82, v128
	v_cvt_pk_bf16_f32 v60, v60, v61
	v_cvt_pk_bf16_f32 v61, v62, v63
	v_cvt_pk_bf16_f32 v52, v52, v53
	v_cvt_pk_bf16_f32 v53, v54, v55
	v_cvt_pk_bf16_f32 v56, v56, v57
	v_cvt_pk_bf16_f32 v57, v58, v59
	v_cvt_pk_bf16_f32 v48, v48, v49
	v_cvt_pk_bf16_f32 v49, v50, v51
	v_cvt_pk_bf16_f32 v44, v44, v45
	v_cvt_pk_bf16_f32 v45, v46, v47
	v_cvt_pk_bf16_f32 v32, v32, v33
	v_cvt_pk_bf16_f32 v33, v34, v35
	v_cvt_pk_bf16_f32 v36, v36, v37
	v_cvt_pk_bf16_f32 v37, v38, v39
	v_cvt_pk_bf16_f32 v24, v24, v25
	v_cvt_pk_bf16_f32 v25, v26, v27
	v_cvt_pk_bf16_f32 v40, v40, v41
	v_cvt_pk_bf16_f32 v41, v42, v43
	v_cvt_pk_bf16_f32 v28, v28, v29
	v_cvt_pk_bf16_f32 v29, v30, v31
	v_cvt_pk_bf16_f32 v20, v20, v21
	v_cvt_pk_bf16_f32 v21, v22, v23
	v_cvt_pk_bf16_f32 v16, v16, v17
	v_cvt_pk_bf16_f32 v17, v18, v19
	v_cvt_pk_bf16_f32 v12, v12, v13
	v_cvt_pk_bf16_f32 v13, v14, v15
	v_cvt_pk_bf16_f32 v8, v8, v9
	v_cvt_pk_bf16_f32 v9, v10, v11
	v_cvt_pk_bf16_f32 v4, v4, v5
	v_cvt_pk_bf16_f32 v5, v6, v7
	v_cvt_pk_bf16_f32 v0, v0, v1
	v_cvt_pk_bf16_f32 v1, v2, v3
	v_mul_u32_u24_e32 v62, 0x110, v130
	v_lshl_add_u32 v62, v128, 1, v62
	v_add_u32_e32 v54, 0x8000, v62
	ds_write2_b64 v54, v[60:61], v[52:53] offset1:4
	v_add_u32_e32 v50, 0x9000, v62
	ds_write2_b64 v50, v[56:57], v[48:49] offset0:32 offset1:36
	ds_write2_b64 v54, v[44:45], v[32:33] offset0:8 offset1:12
	ds_write2_b64 v50, v[36:37], v[24:25] offset0:40 offset1:44
	v_add_u32_e32 v26, 0x1a000, v62
	ds_write_b64 v26, v[40:41]
	ds_write_b64 v26, v[28:29] offset:4352
	v_add_u32_e32 v22, 0x1a020, v62
	ds_write_b64 v22, v[20:21]
	ds_write_b64 v22, v[16:17] offset:4352
	v_add_u32_e32 v14, 0x1a040, v62
	ds_write_b64 v14, v[12:13]
	ds_write_b64 v14, v[8:9] offset:4352
	v_add_u32_e32 v6, 0x1a060, v62
	ds_write_b64 v6, v[4:5]
	s_lshl_b32 s59, s87, 1
	ds_write_b64 v6, v[0:1] offset:4352
	s_nop 0
	v_ashrrev_i32_e32 v132, 8, v137
	v_add_u32_e32 v130, s59, v132
	v_bfe_u32 v135, v137, 7, 1
	v_ashrrev_i32_e32 v131, 31, v130
	v_and_b32_e32 v2, 31, v137
	v_lshlrev_b64 v[0:1], 7, v[130:131]
	v_lshlrev_b32_e32 v136, 6, v135
	v_or3_b32 v0, v0, v136, v2
	v_bfe_u32 v133, v137, 5, 1
	v_lshlrev_b64 v[0:1], 8, v[0:1]
	v_lshl_add_u64 v[0:1], s[4:5], 0, v[0:1]
	v_lshlrev_b32_e32 v128, 4, v133
	v_lshl_add_u64 v[8:9], v[0:1], 0, v[128:129]
	global_load_dwordx4 v[0:3], v[8:9], off
	v_add_co_u32_e32 v10, vcc, s76, v8
	v_mul_i32_i24_e32 v131, 0x12000, v132
	s_nop 0
	v_addc_co_u32_e32 v11, vcc, 0, v9, vcc
	global_load_dwordx4 v[4:7], v[10:11], off
	global_load_dwordx4 v[138:141], v[8:9], off offset:32
	global_load_dwordx4 v[142:145], v[10:11], off offset:32
	global_load_dwordx4 v[146:149], v[8:9], off offset:64
	global_load_dwordx4 v[150:153], v[8:9], off offset:96
	global_load_dwordx4 v[154:157], v[10:11], off offset:64
	global_load_dwordx4 v[158:161], v[10:11], off offset:96
	global_load_dwordx4 v[162:165], v[8:9], off offset:128
	global_load_dwordx4 v[166:169], v[8:9], off offset:160
	global_load_dwordx4 v[170:173], v[10:11], off offset:128
	global_load_dwordx4 v[178:181], v[10:11], off offset:160
	global_load_dwordx4 v[182:185], v[8:9], off offset:192
	global_load_dwordx4 v[186:189], v[8:9], off offset:224
	global_load_dwordx4 v[190:193], v[10:11], off offset:192
	global_load_dwordx4 v[194:197], v[10:11], off offset:224
	v_and_b32_e32 v8, 0x5f, v137
	v_mul_u32_u24_e32 v8, 0x110, v8
	v_add3_u32 v128, v131, v8, v128
	s_waitcnt lgkmcnt(0)
	s_barrier
	ds_read_b128 v[8:11], v128 offset:32768
	ds_read_b128 v[198:201], v128 offset:32800
	s_waitcnt vmcnt(15) lgkmcnt(1)
	v_mfma_f32_32x32x16_bf16 v[32:47], v[0:3], v[8:11], 0
	ds_read_b128 v[12:15], v128 offset:41472
	ds_read_b128 v[202:205], v128 offset:41504
	v_lshlrev_b32_e32 v135, 1, v135
	s_waitcnt vmcnt(14)
	v_mfma_f32_32x32x16_bf16 v[48:63], v[4:7], v[8:11], 0
	s_waitcnt lgkmcnt(1)
	v_mfma_f32_32x32x16_bf16 v[16:31], v[0:3], v[12:15], 0
	v_mfma_f32_32x32x16_bf16 v[0:15], v[4:7], v[12:15], 0
	s_waitcnt vmcnt(13)
	v_mfma_f32_32x32x16_bf16 v[32:47], v[138:141], v[198:201], v[32:47]
	s_waitcnt vmcnt(12)
	v_mfma_f32_32x32x16_bf16 v[48:63], v[142:145], v[198:201], v[48:63]
	s_waitcnt lgkmcnt(0)
	v_mfma_f32_32x32x16_bf16 v[16:31], v[138:141], v[202:205], v[16:31]
	v_mfma_f32_32x32x16_bf16 v[0:15], v[142:145], v[202:205], v[0:15]
	ds_read_b128 v[138:141], v128 offset:32832
	ds_read_b128 v[142:145], v128 offset:32864
	ds_read_b128 v[198:201], v128 offset:41536
	ds_read_b128 v[202:205], v128 offset:41568
	s_waitcnt vmcnt(11) lgkmcnt(3)
	v_mfma_f32_32x32x16_bf16 v[32:47], v[146:149], v[138:141], v[32:47]
	s_waitcnt vmcnt(9)
	v_mfma_f32_32x32x16_bf16 v[48:63], v[154:157], v[138:141], v[48:63]
	s_waitcnt lgkmcnt(1)
	v_mfma_f32_32x32x16_bf16 v[16:31], v[146:149], v[198:201], v[16:31]
	v_mfma_f32_32x32x16_bf16 v[0:15], v[154:157], v[198:201], v[0:15]
	v_mfma_f32_32x32x16_bf16 v[32:47], v[150:153], v[142:145], v[32:47]
	s_waitcnt vmcnt(8)
	v_mfma_f32_32x32x16_bf16 v[48:63], v[158:161], v[142:145], v[48:63]
	ds_read_b128 v[138:141], v128 offset:32896
	ds_read_b128 v[142:145], v128 offset:32928
	s_waitcnt lgkmcnt(2)
	v_mfma_f32_32x32x16_bf16 v[16:31], v[150:153], v[202:205], v[16:31]
	ds_read_b128 v[146:149], v128 offset:41600
	ds_read_b128 v[150:153], v128 offset:41632
	v_mfma_f32_32x32x16_bf16 v[0:15], v[158:161], v[202:205], v[0:15]
	s_waitcnt vmcnt(7) lgkmcnt(3)
	v_mfma_f32_32x32x16_bf16 v[32:47], v[162:165], v[138:141], v[32:47]
	s_waitcnt vmcnt(5)
	v_mfma_f32_32x32x16_bf16 v[48:63], v[170:173], v[138:141], v[48:63]
	s_waitcnt lgkmcnt(1)
	v_mfma_f32_32x32x16_bf16 v[16:31], v[162:165], v[146:149], v[16:31]
	v_mfma_f32_32x32x16_bf16 v[0:15], v[170:173], v[146:149], v[0:15]
	v_mfma_f32_32x32x16_bf16 v[32:47], v[166:169], v[142:145], v[32:47]
	s_waitcnt vmcnt(4)
	v_mfma_f32_32x32x16_bf16 v[48:63], v[178:181], v[142:145], v[48:63]
	ds_read_b128 v[138:141], v128 offset:32960
	ds_read_b128 v[142:145], v128 offset:32992
	s_waitcnt lgkmcnt(2)
	v_mfma_f32_32x32x16_bf16 v[16:31], v[166:169], v[150:153], v[16:31]
	v_mfma_f32_32x32x16_bf16 v[0:15], v[178:181], v[150:153], v[0:15]
	ds_read_b128 v[146:149], v128 offset:41664
	ds_read_b128 v[150:153], v128 offset:41696
	v_and_b32_e32 v128, 0xff, v137
	v_cmp_gt_u32_e32 vcc, s77, v128
	s_waitcnt vmcnt(3) lgkmcnt(3)
	v_mfma_f32_32x32x16_bf16 v[32:47], v[182:185], v[138:141], v[32:47]
	s_waitcnt vmcnt(1)
	v_mfma_f32_32x32x16_bf16 v[48:63], v[190:193], v[138:141], v[48:63]
	v_lshlrev_b32_e32 v138, 2, v133
	s_waitcnt lgkmcnt(1)
	v_mfma_f32_32x32x16_bf16 v[16:31], v[182:185], v[146:149], v[16:31]
	v_mfma_f32_32x32x16_bf16 v[0:15], v[190:193], v[146:149], v[0:15]
	v_mfma_f32_32x32x16_bf16 v[32:47], v[186:189], v[142:145], v[32:47]
	s_waitcnt vmcnt(0)
	v_mfma_f32_32x32x16_bf16 v[48:63], v[194:197], v[142:145], v[48:63]
	s_nop 9
	v_ashrrev_i32_e32 v139, 31, v32
	v_ashrrev_i32_e32 v140, 31, v33
	v_ashrrev_i32_e32 v141, 31, v34
	v_ashrrev_i32_e32 v142, 31, v35
	v_ashrrev_i32_e32 v143, 31, v36
	v_ashrrev_i32_e32 v144, 31, v37
	v_ashrrev_i32_e32 v145, 31, v38
	s_waitcnt lgkmcnt(0)
	v_mfma_f32_32x32x16_bf16 v[16:31], v[186:189], v[150:153], v[16:31]
	v_ashrrev_i32_e32 v146, 31, v39
	v_ashrrev_i32_e32 v147, 31, v40
	v_ashrrev_i32_e32 v148, 31, v41
	v_ashrrev_i32_e32 v149, 31, v42
	v_ashrrev_i32_e32 v154, 31, v47
	v_or_b32_e32 v139, 0x80000000, v139
	v_or_b32_e32 v140, 0x80000000, v140
	v_mfma_f32_32x32x16_bf16 v[0:15], v[194:197], v[150:153], v[0:15]
	v_ashrrev_i32_e32 v150, 31, v43
	v_ashrrev_i32_e32 v151, 31, v44
	v_ashrrev_i32_e32 v152, 31, v45
	v_ashrrev_i32_e32 v153, 31, v46
	v_or_b32_e32 v141, 0x80000000, v141
	v_or_b32_e32 v142, 0x80000000, v142
	v_or_b32_e32 v143, 0x80000000, v143
	v_or_b32_e32 v144, 0x80000000, v144
	v_or_b32_e32 v145, 0x80000000, v145
	v_or_b32_e32 v146, 0x80000000, v146
	v_or_b32_e32 v147, 0x80000000, v147
	v_or_b32_e32 v148, 0x80000000, v148
	v_or_b32_e32 v149, 0x80000000, v149
	v_or_b32_e32 v150, 0x80000000, v150
	v_or_b32_e32 v151, 0x80000000, v151
	v_or_b32_e32 v152, 0x80000000, v152
	v_or_b32_e32 v153, 0x80000000, v153
	v_or_b32_e32 v154, 0x80000000, v154
	v_bitop3_b32 v32, v139, s86, v32 bitop3:0x48
	v_ashrrev_i32_e32 v139, 31, v48
	v_bitop3_b32 v33, v140, s86, v33 bitop3:0x48
	v_ashrrev_i32_e32 v140, 31, v49
	v_bitop3_b32 v34, v141, s86, v34 bitop3:0x48
	v_ashrrev_i32_e32 v141, 31, v50
	v_bitop3_b32 v35, v142, s86, v35 bitop3:0x48
	v_ashrrev_i32_e32 v142, 31, v51
	v_bitop3_b32 v36, v143, s86, v36 bitop3:0x48
	v_ashrrev_i32_e32 v143, 31, v52
	v_bitop3_b32 v37, v144, s86, v37 bitop3:0x48
	v_ashrrev_i32_e32 v144, 31, v53
	v_bitop3_b32 v38, v145, s86, v38 bitop3:0x48
	v_ashrrev_i32_e32 v145, 31, v54
	v_bitop3_b32 v39, v146, s86, v39 bitop3:0x48
	v_ashrrev_i32_e32 v146, 31, v55
	v_bitop3_b32 v40, v147, s86, v40 bitop3:0x48
	v_ashrrev_i32_e32 v147, 31, v56
	v_bitop3_b32 v41, v148, s86, v41 bitop3:0x48
	v_ashrrev_i32_e32 v148, 31, v57
	v_bitop3_b32 v42, v149, s86, v42 bitop3:0x48
	v_ashrrev_i32_e32 v149, 31, v58
	v_bitop3_b32 v43, v150, s86, v43 bitop3:0x48
	v_ashrrev_i32_e32 v150, 31, v59
	v_bitop3_b32 v44, v151, s86, v44 bitop3:0x48
	v_ashrrev_i32_e32 v151, 31, v60
	v_bitop3_b32 v45, v152, s86, v45 bitop3:0x48
	v_ashrrev_i32_e32 v152, 31, v61
	v_bitop3_b32 v46, v153, s86, v46 bitop3:0x48
	v_ashrrev_i32_e32 v153, 31, v62
	v_bitop3_b32 v47, v154, s86, v47 bitop3:0x48
	v_ashrrev_i32_e32 v154, 31, v63
	v_bitop3_b32 v48, v139, v48, s85 bitop3:0x36
	v_or_b32_e32 v139, 1, v138
	v_bitop3_b32 v49, v140, v49, s85 bitop3:0x36
	v_or_b32_e32 v140, 2, v138
	v_bitop3_b32 v50, v141, v50, s85 bitop3:0x36
	v_or_b32_e32 v141, 3, v138
	v_bitop3_b32 v51, v142, v51, s85 bitop3:0x36
	v_or_b32_e32 v142, 8, v138
	v_bitop3_b32 v52, v143, v52, s85 bitop3:0x36
	v_or_b32_e32 v143, 9, v138
	v_bitop3_b32 v53, v144, v53, s85 bitop3:0x36
	v_or_b32_e32 v144, 10, v138
	v_bitop3_b32 v54, v145, v54, s85 bitop3:0x36
	v_or_b32_e32 v145, 11, v138
	v_bitop3_b32 v55, v146, v55, s85 bitop3:0x36
	v_or_b32_e32 v146, 16, v138
	v_bitop3_b32 v56, v147, v56, s85 bitop3:0x36
	v_or_b32_e32 v147, 17, v138
	v_bitop3_b32 v57, v148, v57, s85 bitop3:0x36
	v_or_b32_e32 v148, 18, v138
	v_bitop3_b32 v58, v149, v58, s85 bitop3:0x36
	v_or_b32_e32 v149, 19, v138
	v_bitop3_b32 v59, v150, v59, s85 bitop3:0x36
	v_or_b32_e32 v150, 24, v138
	v_bitop3_b32 v60, v151, v60, s85 bitop3:0x36
	v_or_b32_e32 v151, 25, v138
	v_bitop3_b32 v61, v152, v61, s85 bitop3:0x36
	v_or_b32_e32 v152, 26, v138
	v_bitop3_b32 v62, v153, v62, s85 bitop3:0x36
	v_or_b32_e32 v153, 27, v138
	v_bitop3_b32 v63, v154, v63, s85 bitop3:0x36
	v_and_or_b32 v48, v48, s86, v138
	v_and_or_b32 v49, v49, s86, v139
	v_and_or_b32 v50, v50, s86, v140
	v_and_or_b32 v51, v51, s86, v141
	v_and_or_b32 v52, v52, s86, v142
	v_and_or_b32 v53, v53, s86, v143
	v_and_or_b32 v54, v54, s86, v144
	v_and_or_b32 v55, v55, s86, v145
	v_and_or_b32 v56, v56, s86, v146
	v_and_or_b32 v57, v57, s86, v147
	v_and_or_b32 v58, v58, s86, v148
	v_and_or_b32 v59, v59, s86, v149
	v_and_or_b32 v60, v60, s86, v150
	v_and_or_b32 v61, v61, s86, v151
	v_and_or_b32 v62, v62, s86, v152
	v_and_or_b32 v63, v63, s86, v153
	v_or3_b32 v32, v136, v32, v138
	v_or3_b32 v48, v48, v136, 32
	v_or3_b32 v33, v136, v33, v139
	v_or3_b32 v49, v49, v136, 32
	v_or3_b32 v34, v136, v34, v140
	v_or3_b32 v50, v50, v136, 32
	v_or3_b32 v35, v136, v35, v141
	v_or3_b32 v51, v51, v136, 32
	v_or3_b32 v36, v136, v36, v142
	v_or3_b32 v52, v52, v136, 32
	v_or3_b32 v37, v136, v37, v143
	v_or3_b32 v53, v53, v136, 32
	v_or3_b32 v38, v136, v38, v144
	v_or3_b32 v54, v54, v136, 32
	v_or3_b32 v39, v136, v39, v145
	v_or3_b32 v55, v55, v136, 32
	v_or3_b32 v40, v136, v40, v146
	v_or3_b32 v56, v56, v136, 32
	v_or3_b32 v41, v136, v41, v147
	v_or3_b32 v57, v57, v136, 32
	v_or3_b32 v42, v136, v42, v148
	v_or3_b32 v58, v58, v136, 32
	v_or3_b32 v43, v136, v43, v149
	v_or3_b32 v59, v59, v136, 32
	v_or3_b32 v44, v136, v44, v150
	v_or3_b32 v60, v60, v136, 32
	v_or3_b32 v45, v136, v45, v151
	v_or3_b32 v61, v61, v136, 32
	v_or3_b32 v46, v136, v46, v152
	v_or3_b32 v62, v62, v136, 32
	v_or3_b32 v47, v136, v47, v153
	v_or3_b32 v63, v63, v136, 32
	v_max_u32_e32 v154, v32, v45
	v_min_u32_e32 v32, v32, v45
	v_max_u32_e32 v45, v33, v44
	v_min_u32_e32 v33, v33, v44
	v_max_u32_e32 v44, v34, v47
	v_min_u32_e32 v34, v34, v47
	v_max_u32_e32 v47, v35, v46
	v_min_u32_e32 v35, v35, v46
	v_max_u32_e32 v46, v36, v40
	v_min_u32_e32 v36, v36, v40
	v_max_u32_e32 v40, v37, v38
	v_min_u32_e32 v37, v37, v38
	v_max_u32_e32 v38, v39, v43
	v_min_u32_e32 v39, v39, v43
	v_max_u32_e32 v43, v41, v42
	v_min_u32_e32 v41, v41, v42
	v_max_u32_e32 v162, v48, v61
	v_min_u32_e32 v48, v48, v61
	v_max_u32_e32 v61, v49, v60
	v_min_u32_e32 v49, v49, v60
	v_max_u32_e32 v60, v50, v63
	v_min_u32_e32 v50, v50, v63
	v_max_u32_e32 v63, v51, v62
	v_min_u32_e32 v51, v51, v62
	v_max_u32_e32 v62, v52, v56
	v_min_u32_e32 v52, v52, v56
	v_max_u32_e32 v56, v53, v54
	v_min_u32_e32 v53, v53, v54
	v_max_u32_e32 v54, v55, v59
	v_min_u32_e32 v55, v55, v59
	v_max_u32_e32 v59, v57, v58
	v_min_u32_e32 v57, v57, v58
	v_max_u32_e32 v42, v154, v40
	v_min_u32_e32 v40, v154, v40
	v_max_u32_e32 v154, v45, v38
	v_min_u32_e32 v38, v45, v38
	v_max_u32_e32 v45, v44, v43
	v_min_u32_e32 v43, v44, v43
	v_max_u32_e32 v44, v47, v46
	v_min_u32_e32 v46, v47, v46
	v_max_u32_e32 v47, v37, v32
	v_min_u32_e32 v32, v37, v32
	v_max_u32_e32 v37, v36, v35
	v_min_u32_e32 v35, v36, v35
	v_max_u32_e32 v36, v41, v34
	v_min_u32_e32 v34, v41, v34
	v_max_u32_e32 v41, v39, v33
	v_min_u32_e32 v33, v39, v33
	v_max_u32_e32 v58, v162, v56
	v_min_u32_e32 v56, v162, v56
	v_max_u32_e32 v162, v61, v54
	v_min_u32_e32 v54, v61, v54
	v_max_u32_e32 v61, v60, v59
	v_min_u32_e32 v59, v60, v59
	v_max_u32_e32 v60, v63, v62
	v_min_u32_e32 v62, v63, v62
	v_max_u32_e32 v63, v53, v48
	v_min_u32_e32 v48, v53, v48
	v_max_u32_e32 v53, v52, v51
	v_min_u32_e32 v51, v52, v51
	v_max_u32_e32 v52, v57, v50
	v_min_u32_e32 v50, v57, v50
	v_max_u32_e32 v57, v55, v49
	v_min_u32_e32 v49, v55, v49
	v_max_u32_e32 v39, v42, v154
	v_min_u32_e32 v42, v42, v154
	v_max_u32_e32 v154, v45, v44
	v_min_u32_e32 v44, v45, v44
	v_max_u32_e32 v45, v46, v40
	v_min_u32_e32 v40, v46, v40
	v_max_u32_e32 v46, v47, v37
	v_min_u32_e32 v37, v47, v37
	v_max_u32_e32 v47, v38, v43
	v_min_u32_e32 v38, v38, v43
	v_max_u32_e32 v43, v36, v41
	v_min_u32_e32 v36, v36, v41
	v_max_u32_e32 v41, v33, v32
	v_min_u32_e32 v32, v33, v32
	v_max_u32_e32 v33, v35, v34
	v_min_u32_e32 v34, v35, v34
	v_max_u32_e32 v55, v58, v162
	v_min_u32_e32 v58, v58, v162
	v_max_u32_e32 v162, v61, v60
	v_min_u32_e32 v60, v61, v60
	v_max_u32_e32 v61, v62, v56
	v_min_u32_e32 v56, v62, v56
	v_max_u32_e32 v62, v63, v53
	v_min_u32_e32 v53, v63, v53
	v_max_u32_e32 v63, v54, v59
	v_min_u32_e32 v54, v54, v59
	v_max_u32_e32 v59, v52, v57
	v_min_u32_e32 v52, v52, v57
	v_max_u32_e32 v57, v49, v48
	v_min_u32_e32 v48, v49, v48
	v_max_u32_e32 v49, v51, v50
	v_min_u32_e32 v50, v51, v50
	v_min_u32_e32 v35, v39, v154
	v_max_u32_e32 v155, v42, v44
	v_min_u32_e32 v42, v42, v44
	v_max_u32_e32 v44, v45, v43
	v_min_u32_e32 v43, v45, v43
	v_max_u32_e32 v45, v40, v36
	v_min_u32_e32 v36, v40, v36
	v_max_u32_e32 v40, v46, v47
	v_min_u32_e32 v46, v46, v47
	v_max_u32_e32 v47, v37, v38
	v_min_u32_e32 v37, v37, v38
	v_max_u32_e32 v38, v41, v33
	v_min_u32_e32 v33, v41, v33
	v_max_u32_e32 v41, v32, v34
	v_min_u32_e32 v51, v55, v162
	v_max_u32_e32 v163, v58, v60
	v_min_u32_e32 v58, v58, v60
	v_max_u32_e32 v60, v61, v59
	v_min_u32_e32 v59, v61, v59
	v_max_u32_e32 v61, v56, v52
	v_min_u32_e32 v52, v56, v52
	v_max_u32_e32 v56, v62, v63
	v_min_u32_e32 v62, v62, v63
	v_max_u32_e32 v63, v53, v54
	v_min_u32_e32 v53, v53, v54
	v_max_u32_e32 v54, v57, v49
	v_min_u32_e32 v49, v57, v49
	v_max_u32_e32 v57, v48, v50
	v_min_u32_e32 v32, v32, v34
	v_max_u32_e32 v34, v155, v35
	v_min_u32_e32 v35, v155, v35
	v_max_u32_e32 v155, v42, v38
	v_min_u32_e32 v38, v42, v38
	v_max_u32_e32 v42, v44, v40
	v_min_u32_e32 v40, v44, v40
	v_max_u32_e32 v44, v45, v46
	v_min_u32_e32 v45, v45, v46
	v_max_u32_e32 v46, v47, v43
	v_min_u32_e32 v43, v47, v43
	v_max_u32_e32 v47, v37, v36
	v_min_u32_e32 v36, v37, v36
	v_max_u32_e32 v37, v41, v33
	v_min_u32_e32 v48, v48, v50
	v_max_u32_e32 v50, v163, v51
	v_min_u32_e32 v51, v163, v51
	v_max_u32_e32 v163, v58, v54
	v_min_u32_e32 v54, v58, v54
	v_max_u32_e32 v58, v60, v56
	v_min_u32_e32 v56, v60, v56
	v_max_u32_e32 v60, v61, v62
	v_min_u32_e32 v61, v61, v62
	v_max_u32_e32 v62, v63, v59
	v_min_u32_e32 v59, v63, v59
	v_max_u32_e32 v63, v53, v52
	v_min_u32_e32 v52, v53, v52
	v_max_u32_e32 v53, v57, v49
	v_min_u32_e32 v33, v41, v33
	v_max_u32_e32 v156, v35, v40
	v_min_u32_e32 v35, v35, v40
	v_max_u32_e32 v40, v44, v46
	v_min_u32_e32 v44, v44, v46
	v_max_u32_e32 v46, v45, v43
	v_min_u32_e32 v43, v45, v43
	v_max_u32_e32 v45, v47, v37
	v_min_u32_e32 v49, v57, v49
	v_max_u32_e32 v164, v51, v56
	v_min_u32_e32 v51, v51, v56
	v_max_u32_e32 v56, v60, v62
	v_min_u32_e32 v60, v60, v62
	v_max_u32_e32 v62, v61, v59
	v_min_u32_e32 v59, v61, v59
	v_max_u32_e32 v61, v63, v53
	v_min_u32_e32 v37, v47, v37
	v_max_u32_e32 v47, v36, v33
	v_max_u32_e32 v157, v155, v35
	v_min_u32_e32 v35, v155, v35
	v_max_u32_e32 v155, v45, v38
	v_min_u32_e32 v38, v45, v38
	v_min_u32_e32 v53, v63, v53
	v_max_u32_e32 v63, v52, v49
	v_max_u32_e32 v165, v163, v51
	v_min_u32_e32 v51, v163, v51
	v_max_u32_e32 v163, v61, v54
	v_min_u32_e32 v54, v61, v54
	v_min_u32_e32 v41, v34, v42
	v_max_u32_e32 v45, v47, v37
	v_min_u32_e32 v37, v47, v37
	v_max_u32_e32 v47, v157, v40
	v_min_u32_e32 v40, v157, v40
	v_max_u32_e32 v157, v35, v44
	v_min_u32_e32 v35, v35, v44
	v_max_u32_e32 v44, v46, v155
	v_min_u32_e32 v46, v46, v155
	v_max_u32_e32 v155, v43, v38
	v_min_u32_e32 v57, v50, v58
	v_max_u32_e32 v61, v63, v53
	v_min_u32_e32 v53, v63, v53
	v_max_u32_e32 v63, v165, v56
	v_min_u32_e32 v56, v165, v56
	v_max_u32_e32 v165, v51, v60
	v_min_u32_e32 v51, v51, v60
	v_max_u32_e32 v60, v62, v163
	v_min_u32_e32 v62, v62, v163
	v_max_u32_e32 v163, v59, v54
	v_min_u32_e32 v33, v36, v33
	v_min_u32_e32 v36, v156, v41
	v_min_u32_e32 v38, v43, v38
	v_min_u32_e32 v158, v40, v157
	v_max_u32_e32 v159, v44, v35
	v_min_u32_e32 v35, v44, v35
	v_max_u32_e32 v44, v46, v155
	v_min_u32_e32 v49, v52, v49
	v_min_u32_e32 v52, v164, v57
	v_min_u32_e32 v54, v59, v54
	v_min_u32_e32 v166, v56, v165
	v_max_u32_e32 v167, v60, v51
	v_min_u32_e32 v51, v60, v51
	v_max_u32_e32 v60, v62, v163
	v_min_u32_e32 v43, v47, v36
	v_min_u32_e32 v46, v46, v155
	v_min_u32_e32 v155, v45, v38
	v_min_u32_e32 v160, v158, v159
	v_min_u32_e32 v161, v35, v44
	v_min_u32_e32 v59, v63, v52
	v_min_u32_e32 v62, v62, v163
	v_min_u32_e32 v163, v61, v54
	v_min_u32_e32 v168, v166, v167
	v_min_u32_e32 v169, v51, v60
	v_max3_u32 v39, v39, v154, v48
	v_max3_u32 v34, v34, v42, v49
	v_max3_u32 v41, v156, v41, v53
	v_max3_u32 v36, v47, v36, v163
	v_max3_u32 v42, v43, v61, v54
	v_max3_u32 v40, v40, v157, v62
	v_max3_u32 v43, v158, v159, v169
	v_max3_u32 v47, v160, v51, v60
	v_max3_u32 v35, v35, v44, v168
	v_max3_u32 v44, v161, v166, v167
	v_max3_u32 v46, v46, v56, v165
	v_max3_u32 v38, v45, v38, v59
	v_max3_u32 v45, v155, v63, v52
	v_max3_u32 v37, v37, v164, v57
	v_max3_u32 v33, v33, v50, v58
	v_max3_u32 v32, v32, v55, v162
	v_max_u32_e32 v48, v39, v35
	v_min_u32_e32 v35, v39, v35
	v_max_u32_e32 v39, v34, v44
	v_min_u32_e32 v34, v34, v44
	v_max_u32_e32 v44, v41, v46
	v_min_u32_e32 v41, v41, v46
	v_max_u32_e32 v46, v36, v38
	v_min_u32_e32 v36, v36, v38
	v_max_u32_e32 v38, v42, v45
	v_min_u32_e32 v42, v42, v45
	v_max_u32_e32 v45, v40, v37
	v_min_u32_e32 v37, v40, v37
	v_max_u32_e32 v40, v43, v33
	v_min_u32_e32 v33, v43, v33
	v_max_u32_e32 v43, v47, v32
	v_min_u32_e32 v32, v47, v32
	v_max_u32_e32 v47, v48, v38
	v_min_u32_e32 v38, v48, v38
	v_max_u32_e32 v48, v39, v45
	v_min_u32_e32 v39, v39, v45
	v_max_u32_e32 v45, v44, v40
	v_min_u32_e32 v40, v44, v40
	v_max_u32_e32 v44, v46, v43
	v_min_u32_e32 v43, v46, v43
	v_max_u32_e32 v46, v35, v42
	v_min_u32_e32 v35, v35, v42
	v_max_u32_e32 v42, v34, v37
	v_min_u32_e32 v34, v34, v37
	v_max_u32_e32 v37, v41, v33
	v_min_u32_e32 v33, v41, v33
	v_max_u32_e32 v41, v36, v32
	v_min_u32_e32 v32, v36, v32
	v_max_u32_e32 v36, v47, v45
	v_min_u32_e32 v45, v47, v45
	v_max_u32_e32 v47, v48, v44
	v_min_u32_e32 v44, v48, v44
	v_max_u32_e32 v48, v38, v40
	v_min_u32_e32 v40, v38, v40
	v_max_u32_e32 v38, v39, v43
	v_min_u32_e32 v39, v39, v43
	v_max_u32_e32 v43, v46, v37
	v_min_u32_e32 v46, v46, v37
	v_max_u32_e32 v51, v35, v33
	v_min_u32_e32 v52, v35, v33
	v_max_u32_e32 v53, v34, v32
	v_min_u32_e32 v54, v34, v32
	v_max_u32_e32 v32, v36, v47
	v_min_u32_e32 v33, v36, v47
	v_max_u32_e32 v36, v48, v38
	v_min_u32_e32 v37, v48, v38
	v_lshlrev_b32_e32 v48, 2, v137
	v_max_u32_e32 v49, v42, v41
	v_and_b32_e32 v48, 0x17c, v48
	v_min_u32_e32 v50, v42, v41
	v_max_u32_e32 v38, v40, v39
	v_min_u32_e32 v39, v40, v39
	v_max_u32_e32 v40, v43, v49
	v_min_u32_e32 v41, v43, v49
	v_or3_b32 v49, v135, v48, v133
	v_lshlrev_b32_e32 v49, 6, v49
	v_max_u32_e32 v34, v45, v44
	v_min_u32_e32 v35, v45, v44
	v_mad_i32_i24 v49, v132, s75, v49
	v_max_u32_e32 v42, v46, v50
	v_min_u32_e32 v43, v46, v50
	v_max_u32_e32 v44, v51, v53
	v_min_u32_e32 v45, v51, v53
	v_max_u32_e32 v46, v52, v54
	v_min_u32_e32 v47, v52, v54
	v_bfe_u32 v240, v49, 8, 4
	v_lshlrev_b32_e32 v240, 4, v240
	v_xor_b32_e32 v240, v49, v240
	ds_write_b128 v240, v[32:35]
	v_xor_b32_e32 v241, 16, v240
	ds_write_b128 v241, v[36:39]
	v_xor_b32_e32 v241, 32, v240
	ds_write_b128 v241, v[40:43]
	v_xor_b32_e32 v241, 48, v240
	ds_write_b128 v241, v[44:47]
	v_ashrrev_i32_e32 v32, 31, v16
	v_or_b32_e32 v32, 0x80000000, v32
	v_bitop3_b32 v16, v32, s86, v16 bitop3:0x48
	v_ashrrev_i32_e32 v32, 31, v0
	v_bitop3_b32 v0, v32, v0, s85 bitop3:0x36
	v_ashrrev_i32_e32 v32, 31, v17
	v_or_b32_e32 v32, 0x80000000, v32
	v_bitop3_b32 v17, v32, s86, v17 bitop3:0x48
	v_ashrrev_i32_e32 v32, 31, v1
	v_bitop3_b32 v1, v32, v1, s85 bitop3:0x36
	v_ashrrev_i32_e32 v32, 31, v18
	v_or_b32_e32 v32, 0x80000000, v32
	v_bitop3_b32 v18, v32, s86, v18 bitop3:0x48
	v_ashrrev_i32_e32 v32, 31, v2
	v_bitop3_b32 v2, v32, v2, s85 bitop3:0x36
	v_ashrrev_i32_e32 v32, 31, v19
	v_or_b32_e32 v32, 0x80000000, v32
	v_bitop3_b32 v19, v32, s86, v19 bitop3:0x48
	v_ashrrev_i32_e32 v32, 31, v3
	v_bitop3_b32 v3, v32, v3, s85 bitop3:0x36
	v_ashrrev_i32_e32 v32, 31, v20
	v_or_b32_e32 v32, 0x80000000, v32
	v_bitop3_b32 v20, v32, s86, v20 bitop3:0x48
	v_ashrrev_i32_e32 v32, 31, v4
	v_bitop3_b32 v4, v32, v4, s85 bitop3:0x36
	v_ashrrev_i32_e32 v32, 31, v21
	v_or_b32_e32 v32, 0x80000000, v32
	v_bitop3_b32 v21, v32, s86, v21 bitop3:0x48
	v_ashrrev_i32_e32 v32, 31, v5
	v_bitop3_b32 v5, v32, v5, s85 bitop3:0x36
	v_ashrrev_i32_e32 v32, 31, v22
	v_or_b32_e32 v32, 0x80000000, v32
	v_bitop3_b32 v22, v32, s86, v22 bitop3:0x48
	v_ashrrev_i32_e32 v32, 31, v6
	v_bitop3_b32 v6, v32, v6, s85 bitop3:0x36
	v_ashrrev_i32_e32 v32, 31, v23
	v_or_b32_e32 v32, 0x80000000, v32
	v_bitop3_b32 v23, v32, s86, v23 bitop3:0x48
	v_ashrrev_i32_e32 v32, 31, v7
	v_bitop3_b32 v7, v32, v7, s85 bitop3:0x36
	v_ashrrev_i32_e32 v32, 31, v24
	v_or_b32_e32 v32, 0x80000000, v32
	v_bitop3_b32 v24, v32, s86, v24 bitop3:0x48
	v_ashrrev_i32_e32 v32, 31, v8
	v_bitop3_b32 v8, v32, v8, s85 bitop3:0x36
	v_ashrrev_i32_e32 v32, 31, v25
	v_or_b32_e32 v32, 0x80000000, v32
	v_bitop3_b32 v25, v32, s86, v25 bitop3:0x48
	v_ashrrev_i32_e32 v32, 31, v9
	v_bitop3_b32 v9, v32, v9, s85 bitop3:0x36
	v_ashrrev_i32_e32 v32, 31, v26
	v_or_b32_e32 v32, 0x80000000, v32
	v_bitop3_b32 v26, v32, s86, v26 bitop3:0x48
	v_ashrrev_i32_e32 v32, 31, v10
	v_bitop3_b32 v10, v32, v10, s85 bitop3:0x36
	v_ashrrev_i32_e32 v32, 31, v27
	v_or_b32_e32 v32, 0x80000000, v32
	v_bitop3_b32 v27, v32, s86, v27 bitop3:0x48
	v_ashrrev_i32_e32 v32, 31, v11
	v_bitop3_b32 v11, v32, v11, s85 bitop3:0x36
	v_ashrrev_i32_e32 v32, 31, v28
	v_or_b32_e32 v32, 0x80000000, v32
	v_bitop3_b32 v28, v32, s86, v28 bitop3:0x48
	v_ashrrev_i32_e32 v32, 31, v12
	v_bitop3_b32 v12, v32, v12, s85 bitop3:0x36
	v_ashrrev_i32_e32 v32, 31, v29
	v_or_b32_e32 v32, 0x80000000, v32
	v_bitop3_b32 v29, v32, s86, v29 bitop3:0x48
	v_ashrrev_i32_e32 v32, 31, v13
	v_bitop3_b32 v13, v32, v13, s85 bitop3:0x36
	v_ashrrev_i32_e32 v32, 31, v30
	v_or_b32_e32 v32, 0x80000000, v32
	v_bitop3_b32 v30, v32, s86, v30 bitop3:0x48
	v_ashrrev_i32_e32 v32, 31, v14
	v_bitop3_b32 v14, v32, v14, s85 bitop3:0x36
	v_ashrrev_i32_e32 v32, 31, v31
	v_or_b32_e32 v32, 0x80000000, v32
	v_bitop3_b32 v31, v32, s86, v31 bitop3:0x48
	v_ashrrev_i32_e32 v32, 31, v15
	v_bitop3_b32 v15, v32, v15, s85 bitop3:0x36
	v_and_or_b32 v0, v0, s86, v138
	v_and_or_b32 v1, v1, s86, v139
	v_and_or_b32 v2, v2, s86, v140
	v_and_or_b32 v3, v3, s86, v141
	v_and_or_b32 v4, v4, s86, v142
	v_and_or_b32 v5, v5, s86, v143
	v_and_or_b32 v6, v6, s86, v144
	v_and_or_b32 v7, v7, s86, v145
	v_and_or_b32 v8, v8, s86, v146
	v_and_or_b32 v9, v9, s86, v147
	v_and_or_b32 v10, v10, s86, v148
	v_and_or_b32 v11, v11, s86, v149
	v_and_or_b32 v12, v12, s86, v150
	v_and_or_b32 v13, v13, s86, v151
	v_and_or_b32 v14, v14, s86, v152
	v_and_or_b32 v15, v15, s86, v153
	v_or3_b32 v16, v136, v16, v138
	v_or3_b32 v0, v0, v136, 32
	v_or3_b32 v17, v136, v17, v139
	v_or3_b32 v1, v1, v136, 32
	v_or3_b32 v18, v136, v18, v140
	v_or3_b32 v2, v2, v136, 32
	v_or3_b32 v19, v136, v19, v141
	v_or3_b32 v3, v3, v136, 32
	v_or3_b32 v20, v136, v20, v142
	v_or3_b32 v4, v4, v136, 32
	v_or3_b32 v21, v136, v21, v143
	v_or3_b32 v5, v5, v136, 32
	v_or3_b32 v22, v136, v22, v144
	v_or3_b32 v6, v6, v136, 32
	v_or3_b32 v23, v136, v23, v145
	v_or3_b32 v7, v7, v136, 32
	v_or3_b32 v24, v136, v24, v146
	v_or3_b32 v8, v8, v136, 32
	v_or3_b32 v25, v136, v25, v147
	v_or3_b32 v9, v9, v136, 32
	v_or3_b32 v26, v136, v26, v148
	v_or3_b32 v10, v10, v136, 32
	v_or3_b32 v27, v136, v27, v149
	v_or3_b32 v11, v11, v136, 32
	v_or3_b32 v28, v136, v28, v150
	v_or3_b32 v12, v12, v136, 32
	v_or3_b32 v29, v136, v29, v151
	v_or3_b32 v13, v13, v136, 32
	v_or3_b32 v30, v136, v30, v152
	v_or3_b32 v14, v14, v136, 32
	v_or3_b32 v31, v136, v31, v153
	v_or3_b32 v15, v15, v136, 32
	v_max_u32_e32 v32, v16, v29
	v_min_u32_e32 v16, v16, v29
	v_max_u32_e32 v29, v17, v28
	v_min_u32_e32 v17, v17, v28
	v_max_u32_e32 v28, v18, v31
	v_min_u32_e32 v18, v18, v31
	v_max_u32_e32 v31, v19, v30
	v_min_u32_e32 v19, v19, v30
	v_max_u32_e32 v30, v20, v24
	v_min_u32_e32 v20, v20, v24
	v_max_u32_e32 v24, v21, v22
	v_min_u32_e32 v21, v21, v22
	v_max_u32_e32 v22, v23, v27
	v_min_u32_e32 v23, v23, v27
	v_max_u32_e32 v27, v25, v26
	v_min_u32_e32 v25, v25, v26
	v_max_u32_e32 v40, v0, v13
	v_min_u32_e32 v0, v0, v13
	v_max_u32_e32 v13, v1, v12
	v_min_u32_e32 v1, v1, v12
	v_max_u32_e32 v12, v2, v15
	v_min_u32_e32 v2, v2, v15
	v_max_u32_e32 v15, v3, v14
	v_min_u32_e32 v3, v3, v14
	v_max_u32_e32 v14, v4, v8
	v_min_u32_e32 v4, v4, v8
	v_max_u32_e32 v8, v5, v6
	v_min_u32_e32 v5, v5, v6
	v_max_u32_e32 v6, v7, v11
	v_min_u32_e32 v7, v7, v11
	v_max_u32_e32 v11, v9, v10
	v_min_u32_e32 v9, v9, v10
	v_max_u32_e32 v26, v32, v24
	v_min_u32_e32 v24, v32, v24
	v_max_u32_e32 v32, v29, v22
	v_min_u32_e32 v22, v29, v22
	v_max_u32_e32 v29, v28, v27
	v_min_u32_e32 v27, v28, v27
	v_max_u32_e32 v28, v31, v30
	v_min_u32_e32 v30, v31, v30
	v_max_u32_e32 v31, v21, v16
	v_min_u32_e32 v16, v21, v16
	v_max_u32_e32 v21, v20, v19
	v_min_u32_e32 v19, v20, v19
	v_max_u32_e32 v20, v25, v18
	v_min_u32_e32 v18, v25, v18
	v_max_u32_e32 v25, v23, v17
	v_min_u32_e32 v17, v23, v17
	v_max_u32_e32 v10, v40, v8
	v_min_u32_e32 v8, v40, v8
	v_max_u32_e32 v40, v13, v6
	v_min_u32_e32 v6, v13, v6
	v_max_u32_e32 v13, v12, v11
	v_min_u32_e32 v11, v12, v11
	v_max_u32_e32 v12, v15, v14
	v_min_u32_e32 v14, v15, v14
	v_max_u32_e32 v15, v5, v0
	v_min_u32_e32 v0, v5, v0
	v_max_u32_e32 v5, v4, v3
	v_min_u32_e32 v3, v4, v3
	v_max_u32_e32 v4, v9, v2
	v_min_u32_e32 v2, v9, v2
	v_max_u32_e32 v9, v7, v1
	v_min_u32_e32 v1, v7, v1
	v_max_u32_e32 v23, v26, v32
	v_min_u32_e32 v26, v26, v32
	v_max_u32_e32 v32, v29, v28
	v_min_u32_e32 v28, v29, v28
	v_max_u32_e32 v29, v30, v24
	v_min_u32_e32 v24, v30, v24
	v_max_u32_e32 v30, v31, v21
	v_min_u32_e32 v21, v31, v21
	v_max_u32_e32 v31, v22, v27
	v_min_u32_e32 v22, v22, v27
	v_max_u32_e32 v27, v20, v25
	v_min_u32_e32 v20, v20, v25
	v_max_u32_e32 v25, v17, v16
	v_min_u32_e32 v16, v17, v16
	v_max_u32_e32 v17, v19, v18
	v_min_u32_e32 v18, v19, v18
	v_max_u32_e32 v7, v10, v40
	v_min_u32_e32 v10, v10, v40
	v_max_u32_e32 v40, v13, v12
	v_min_u32_e32 v12, v13, v12
	v_max_u32_e32 v13, v14, v8
	v_min_u32_e32 v8, v14, v8
	v_max_u32_e32 v14, v15, v5
	v_min_u32_e32 v5, v15, v5
	v_max_u32_e32 v15, v6, v11
	v_min_u32_e32 v6, v6, v11
	v_max_u32_e32 v11, v4, v9
	v_min_u32_e32 v4, v4, v9
	v_max_u32_e32 v9, v1, v0
	v_min_u32_e32 v0, v1, v0
	v_max_u32_e32 v1, v3, v2
	v_min_u32_e32 v2, v3, v2
	v_min_u32_e32 v19, v23, v32
	v_max_u32_e32 v33, v26, v28
	v_min_u32_e32 v26, v26, v28
	v_max_u32_e32 v28, v29, v27
	v_min_u32_e32 v27, v29, v27
	v_max_u32_e32 v29, v24, v20
	v_min_u32_e32 v20, v24, v20
	v_max_u32_e32 v24, v30, v31
	v_min_u32_e32 v30, v30, v31
	v_max_u32_e32 v31, v21, v22
	v_min_u32_e32 v21, v21, v22
	v_max_u32_e32 v22, v25, v17
	v_min_u32_e32 v17, v25, v17
	v_max_u32_e32 v25, v16, v18
	v_min_u32_e32 v3, v7, v40
	v_max_u32_e32 v41, v10, v12
	v_min_u32_e32 v10, v10, v12
	v_max_u32_e32 v12, v13, v11
	v_min_u32_e32 v11, v13, v11
	v_max_u32_e32 v13, v8, v4
	v_min_u32_e32 v4, v8, v4
	v_max_u32_e32 v8, v14, v15
	v_min_u32_e32 v14, v14, v15
	v_max_u32_e32 v15, v5, v6
	v_min_u32_e32 v5, v5, v6
	v_max_u32_e32 v6, v9, v1
	v_min_u32_e32 v1, v9, v1
	v_max_u32_e32 v9, v0, v2
	v_min_u32_e32 v16, v16, v18
	v_max_u32_e32 v18, v33, v19
	v_min_u32_e32 v19, v33, v19
	v_max_u32_e32 v33, v26, v22
	v_min_u32_e32 v22, v26, v22
	v_max_u32_e32 v26, v28, v24
	v_min_u32_e32 v24, v28, v24
	v_max_u32_e32 v28, v29, v30
	v_min_u32_e32 v29, v29, v30
	v_max_u32_e32 v30, v31, v27
	v_min_u32_e32 v27, v31, v27
	v_max_u32_e32 v31, v21, v20
	v_min_u32_e32 v20, v21, v20
	v_max_u32_e32 v21, v25, v17
	v_min_u32_e32 v0, v0, v2
	v_max_u32_e32 v2, v41, v3
	v_min_u32_e32 v3, v41, v3
	v_max_u32_e32 v41, v10, v6
	v_min_u32_e32 v6, v10, v6
	v_max_u32_e32 v10, v12, v8
	v_min_u32_e32 v8, v12, v8
	v_max_u32_e32 v12, v13, v14
	v_min_u32_e32 v13, v13, v14
	v_max_u32_e32 v14, v15, v11
	v_min_u32_e32 v11, v15, v11
	v_max_u32_e32 v15, v5, v4
	v_min_u32_e32 v4, v5, v4
	v_max_u32_e32 v5, v9, v1
	v_min_u32_e32 v17, v25, v17
	v_max_u32_e32 v34, v19, v24
	v_min_u32_e32 v19, v19, v24
	v_max_u32_e32 v24, v28, v30
	v_min_u32_e32 v28, v28, v30
	v_max_u32_e32 v30, v29, v27
	v_min_u32_e32 v27, v29, v27
	v_max_u32_e32 v29, v31, v21
	v_min_u32_e32 v1, v9, v1
	v_max_u32_e32 v42, v3, v8
	v_min_u32_e32 v3, v3, v8
	v_max_u32_e32 v8, v12, v14
	v_min_u32_e32 v12, v12, v14
	v_max_u32_e32 v14, v13, v11
	v_min_u32_e32 v11, v13, v11
	v_max_u32_e32 v13, v15, v5
	v_min_u32_e32 v21, v31, v21
	v_max_u32_e32 v31, v20, v17
	v_max_u32_e32 v35, v33, v19
	v_min_u32_e32 v19, v33, v19
	v_max_u32_e32 v33, v29, v22
	v_min_u32_e32 v22, v29, v22
	v_min_u32_e32 v5, v15, v5
	v_max_u32_e32 v15, v4, v1
	v_max_u32_e32 v43, v41, v3
	v_min_u32_e32 v3, v41, v3
	v_max_u32_e32 v41, v13, v6
	v_min_u32_e32 v6, v13, v6
	v_min_u32_e32 v25, v18, v26
	v_max_u32_e32 v29, v31, v21
	v_min_u32_e32 v21, v31, v21
	v_max_u32_e32 v31, v35, v24
	v_min_u32_e32 v24, v35, v24
	v_max_u32_e32 v35, v19, v28
	v_min_u32_e32 v19, v19, v28
	v_max_u32_e32 v28, v30, v33
	v_min_u32_e32 v30, v30, v33
	v_max_u32_e32 v33, v27, v22
	v_min_u32_e32 v9, v2, v10
	v_max_u32_e32 v13, v15, v5
	v_min_u32_e32 v5, v15, v5
	v_max_u32_e32 v15, v43, v8
	v_min_u32_e32 v8, v43, v8
	v_max_u32_e32 v43, v3, v12
	v_min_u32_e32 v3, v3, v12
	v_max_u32_e32 v12, v14, v41
	v_min_u32_e32 v14, v14, v41
	v_max_u32_e32 v41, v11, v6
	v_min_u32_e32 v17, v20, v17
	v_min_u32_e32 v20, v34, v25
	v_min_u32_e32 v22, v27, v22
	v_min_u32_e32 v36, v24, v35
	v_max_u32_e32 v37, v28, v19
	v_min_u32_e32 v19, v28, v19
	v_max_u32_e32 v28, v30, v33
	v_min_u32_e32 v1, v4, v1
	v_min_u32_e32 v4, v42, v9
	v_min_u32_e32 v6, v11, v6
	v_min_u32_e32 v44, v8, v43
	v_max_u32_e32 v45, v12, v3
	v_min_u32_e32 v3, v12, v3
	v_max_u32_e32 v12, v14, v41
	v_min_u32_e32 v27, v31, v20
	v_min_u32_e32 v30, v30, v33
	v_min_u32_e32 v33, v29, v22
	v_min_u32_e32 v38, v36, v37
	v_min_u32_e32 v39, v19, v28
	v_min_u32_e32 v11, v15, v4
	v_min_u32_e32 v14, v14, v41
	v_min_u32_e32 v41, v13, v6
	v_min_u32_e32 v46, v44, v45
	v_min_u32_e32 v47, v3, v12
	v_max3_u32 v0, v23, v32, v0
	v_max3_u32 v1, v18, v26, v1
	v_max3_u32 v5, v34, v25, v5
	v_max3_u32 v18, v31, v20, v41
	v_max3_u32 v6, v27, v13, v6
	v_max3_u32 v13, v24, v35, v14
	v_max3_u32 v14, v36, v37, v47
	v_max3_u32 v3, v38, v3, v12
	v_max3_u32 v12, v19, v28, v46
	v_max3_u32 v19, v39, v44, v45
	v_max3_u32 v8, v30, v8, v43
	v_max3_u32 v11, v29, v22, v11
	v_max3_u32 v4, v33, v15, v4
	v_max3_u32 v9, v21, v42, v9
	v_max3_u32 v2, v17, v2, v10
	v_max3_u32 v7, v16, v7, v40
	v_max_u32_e32 v10, v0, v12
	v_min_u32_e32 v0, v0, v12
	v_max_u32_e32 v12, v1, v19
	v_max_u32_e32 v15, v5, v8
	v_min_u32_e32 v5, v5, v8
	v_max_u32_e32 v8, v18, v11
	v_max_u32_e32 v16, v6, v4
	v_min_u32_e32 v4, v6, v4
	v_max_u32_e32 v6, v13, v9
	v_min_u32_e32 v9, v13, v9
	v_max_u32_e32 v13, v14, v2
	v_min_u32_e32 v2, v14, v2
	v_max_u32_e32 v14, v3, v7
	v_min_u32_e32 v1, v1, v19
	v_min_u32_e32 v11, v18, v11
	v_min_u32_e32 v3, v3, v7
	v_max_u32_e32 v7, v10, v16
	v_min_u32_e32 v10, v10, v16
	v_max_u32_e32 v16, v12, v6
	v_min_u32_e32 v6, v12, v6
	v_max_u32_e32 v12, v15, v13
	v_min_u32_e32 v13, v15, v13
	v_max_u32_e32 v15, v8, v14
	v_min_u32_e32 v8, v8, v14
	v_max_u32_e32 v14, v0, v4
	v_min_u32_e32 v0, v0, v4
	v_max_u32_e32 v4, v1, v9
	v_min_u32_e32 v1, v1, v9
	v_max_u32_e32 v9, v5, v2
	v_min_u32_e32 v2, v5, v2
	v_max_u32_e32 v5, v11, v3
	v_min_u32_e32 v3, v11, v3
	v_max_u32_e32 v11, v7, v12
	v_min_u32_e32 v7, v7, v12
	v_max_u32_e32 v12, v16, v15
	v_min_u32_e32 v15, v16, v15
	v_max_u32_e32 v16, v10, v13
	v_min_u32_e32 v10, v10, v13
	v_max_u32_e32 v13, v6, v8
	v_max_u32_e32 v17, v14, v9
	v_min_u32_e32 v14, v14, v9
	v_max_u32_e32 v9, v4, v5
	v_min_u32_e32 v18, v4, v5
	v_max_u32_e32 v4, v16, v13
	v_min_u32_e32 v5, v16, v13
	v_or3_b32 v16, v133, v48, v135
	v_lshlrev_b32_e32 v16, 6, v16
	v_min_u32_e32 v8, v6, v8
	v_max_u32_e32 v19, v0, v2
	v_min_u32_e32 v20, v0, v2
	v_max_u32_e32 v21, v1, v3
	v_min_u32_e32 v22, v1, v3
	v_max_u32_e32 v0, v11, v12
	v_min_u32_e32 v1, v11, v12
	v_max_u32_e32 v2, v7, v15
	v_min_u32_e32 v3, v7, v15
	v_mad_i32_i24 v16, v132, s75, v16
	v_max_u32_e32 v6, v10, v8
	v_min_u32_e32 v7, v10, v8
	v_max_u32_e32 v8, v17, v9
	v_min_u32_e32 v9, v17, v9
	v_max_u32_e32 v10, v14, v18
	v_min_u32_e32 v11, v14, v18
	v_max_u32_e32 v12, v19, v21
	v_min_u32_e32 v13, v19, v21
	v_max_u32_e32 v14, v20, v22
	v_min_u32_e32 v15, v20, v22
	v_bfe_u32 v240, v16, 8, 4
	v_lshlrev_b32_e32 v240, 4, v240
	v_xor_b32_e32 v240, v16, v240
	ds_write_b128 v240, v[0:3] offset:8192
	v_xor_b32_e32 v241, 16, v240
	ds_write_b128 v241, v[4:7] offset:8192
	v_xor_b32_e32 v241, 32, v240
	ds_write_b128 v241, v[8:11] offset:8192
	v_xor_b32_e32 v241, 48, v240
	ds_write_b128 v241, v[12:15] offset:8192
	s_waitcnt lgkmcnt(0)
	s_barrier
	s_and_saveexec_b64 s[62:63], vcc
	s_cbranch_execz .LBB0_867
	v_lshl_add_u32 v60, v128, 8, v131
	v_bfe_u32 v240, v60, 8, 4
	v_lshlrev_b32_e32 v240, 4, v240
	v_xor_b32_e32 v240, v60, v240
	ds_read_b128 v[0:3], v240
	v_xor_b32_e32 v241, 16, v240
	ds_read_b128 v[4:7], v241
	v_xor_b32_e32 v241, 32, v240
	ds_read_b128 v[8:11], v241
	v_xor_b32_e32 v241, 48, v240
	ds_read_b128 v[12:15], v241
	v_xor_b32_e32 v241, 64, v240
	ds_read_b128 v[16:19], v241
	v_xor_b32_e32 v241, 0x50, v240
	ds_read_b128 v[20:23], v241
	v_xor_b32_e32 v241, 0x80, v240
	ds_read_b128 v[24:27], v241
	v_xor_b32_e32 v241, 0x90, v240
	ds_read_b128 v[28:31], v241
	v_xor_b32_e32 v241, 0xc0, v240
	ds_read_b128 v[32:35], v241
	v_xor_b32_e32 v241, 0xd0, v240
	ds_read_b128 v[36:39], v241
	v_xor_b32_e32 v241, 0x60, v240
	ds_read_b128 v[40:43], v241
	v_xor_b32_e32 v241, 0x70, v240
	ds_read_b128 v[44:47], v241
	v_xor_b32_e32 v241, 0xa0, v240
	ds_read_b128 v[48:51], v241
	v_xor_b32_e32 v241, 0xb0, v240
	ds_read_b128 v[52:55], v241
	v_xor_b32_e32 v241, 0xe0, v240
	ds_read_b128 v[56:59], v241
	v_xor_b32_e32 v241, 0xf0, v240
	ds_read_b128 v[60:63], v241
	s_waitcnt lgkmcnt(4)
	v_max_u32_e32 v0, v0, v47
	v_max_u32_e32 v1, v1, v46
	v_max_u32_e32 v2, v2, v45
	v_max_u32_e32 v3, v3, v44
	v_max_u32_e32 v4, v4, v43
	v_max_u32_e32 v5, v5, v42
	v_max_u32_e32 v6, v6, v41
	v_max_u32_e32 v7, v7, v40
	v_max_u32_e32 v8, v8, v23
	v_max_u32_e32 v9, v9, v22
	v_max_u32_e32 v10, v10, v21
	v_max_u32_e32 v11, v11, v20
	v_max_u32_e32 v12, v12, v19
	v_max_u32_e32 v13, v13, v18
	v_max_u32_e32 v14, v14, v17
	v_max_u32_e32 v15, v15, v16
	s_waitcnt lgkmcnt(0)
	v_max_u32_e32 v24, v24, v63
	v_max_u32_e32 v25, v25, v62
	v_max_u32_e32 v26, v26, v61
	v_max_u32_e32 v27, v27, v60
	v_max_u32_e32 v28, v28, v59
	v_max_u32_e32 v29, v29, v58
	v_max_u32_e32 v30, v30, v57
	v_max_u32_e32 v31, v31, v56
	v_max_u32_e32 v39, v48, v39
	v_max_u32_e32 v38, v49, v38
	v_max_u32_e32 v37, v50, v37
	v_max_u32_e32 v36, v51, v36
	v_max_u32_e32 v35, v52, v35
	v_max_u32_e32 v34, v53, v34
	v_max_u32_e32 v33, v54, v33
	v_max_u32_e32 v32, v55, v32
	v_max_u32_e32 v16, v0, v8
	v_min_u32_e32 v0, v0, v8
	v_max_u32_e32 v8, v1, v9
	v_min_u32_e32 v1, v1, v9
	v_max_u32_e32 v9, v2, v10
	v_min_u32_e32 v2, v2, v10
	v_max_u32_e32 v10, v3, v11
	v_min_u32_e32 v3, v3, v11
	v_max_u32_e32 v11, v4, v12
	v_min_u32_e32 v4, v4, v12
	v_max_u32_e32 v12, v5, v13
	v_min_u32_e32 v5, v5, v13
	v_max_u32_e32 v13, v6, v14
	v_min_u32_e32 v6, v6, v14
	v_max_u32_e32 v14, v7, v15
	v_min_u32_e32 v7, v7, v15
	v_max_u32_e32 v40, v24, v39
	v_min_u32_e32 v24, v24, v39
	v_max_u32_e32 v39, v25, v38
	v_min_u32_e32 v25, v25, v38
	v_max_u32_e32 v38, v26, v37
	v_min_u32_e32 v26, v26, v37
	v_max_u32_e32 v37, v27, v36
	v_min_u32_e32 v27, v27, v36
	v_max_u32_e32 v36, v28, v35
	v_min_u32_e32 v28, v28, v35
	v_max_u32_e32 v35, v29, v34
	v_min_u32_e32 v29, v29, v34
	v_max_u32_e32 v34, v30, v33
	v_min_u32_e32 v30, v30, v33
	v_max_u32_e32 v33, v31, v32
	v_min_u32_e32 v31, v31, v32
	v_max_u32_e32 v15, v16, v11
	v_min_u32_e32 v11, v16, v11
	v_max_u32_e32 v16, v8, v12
	v_min_u32_e32 v8, v8, v12
	v_max_u32_e32 v12, v9, v13
	v_min_u32_e32 v9, v9, v13
	v_max_u32_e32 v13, v10, v14
	v_min_u32_e32 v10, v10, v14
	v_max_u32_e32 v14, v0, v4
	v_min_u32_e32 v0, v0, v4
	v_max_u32_e32 v4, v1, v5
	v_min_u32_e32 v1, v1, v5
	v_max_u32_e32 v5, v2, v6
	v_min_u32_e32 v2, v2, v6
	v_max_u32_e32 v6, v3, v7
	v_min_u32_e32 v3, v3, v7
	v_max_u32_e32 v32, v40, v36
	v_min_u32_e32 v36, v40, v36
	v_max_u32_e32 v40, v39, v35
	v_min_u32_e32 v35, v39, v35
	v_max_u32_e32 v39, v38, v34
	v_min_u32_e32 v34, v38, v34
	v_max_u32_e32 v38, v37, v33
	v_min_u32_e32 v33, v37, v33
	v_max_u32_e32 v37, v24, v28
	v_min_u32_e32 v24, v24, v28
	v_max_u32_e32 v28, v25, v29
	v_min_u32_e32 v25, v25, v29
	v_max_u32_e32 v29, v26, v30
	v_min_u32_e32 v26, v26, v30
	v_max_u32_e32 v30, v27, v31
	v_min_u32_e32 v27, v27, v31
	v_max_u32_e32 v7, v15, v12
	v_min_u32_e32 v12, v15, v12
	v_max_u32_e32 v15, v16, v13
	v_min_u32_e32 v13, v16, v13
	v_max_u32_e32 v16, v11, v9
	v_min_u32_e32 v9, v11, v9
	v_max_u32_e32 v11, v8, v10
	v_min_u32_e32 v8, v8, v10
	v_max_u32_e32 v10, v14, v5
	v_min_u32_e32 v5, v14, v5
	v_max_u32_e32 v14, v4, v6
	v_min_u32_e32 v4, v4, v6
	v_max_u32_e32 v6, v0, v2
	v_min_u32_e32 v0, v0, v2
	v_max_u32_e32 v2, v1, v3
	v_min_u32_e32 v1, v1, v3
	v_max_u32_e32 v31, v32, v39
	v_min_u32_e32 v32, v32, v39
	v_max_u32_e32 v39, v40, v38
	v_min_u32_e32 v38, v40, v38
	v_max_u32_e32 v40, v36, v34
	v_min_u32_e32 v34, v36, v34
	v_max_u32_e32 v36, v35, v33
	v_min_u32_e32 v33, v35, v33
	v_max_u32_e32 v35, v37, v29
	v_min_u32_e32 v29, v37, v29
	v_max_u32_e32 v37, v28, v30
	v_min_u32_e32 v28, v28, v30
	v_max_u32_e32 v30, v24, v26
	v_min_u32_e32 v24, v24, v26
	v_max_u32_e32 v26, v25, v27
	v_min_u32_e32 v25, v25, v27
	v_min_u32_e32 v3, v7, v15
	v_min_u32_e32 v17, v12, v13
	v_min_u32_e32 v18, v16, v11
	v_min_u32_e32 v19, v9, v8
	v_min_u32_e32 v20, v10, v14
	v_min_u32_e32 v21, v5, v4
	v_min_u32_e32 v22, v6, v2
	v_min_u32_e32 v23, v0, v1
	v_min_u32_e32 v27, v31, v39
	v_min_u32_e32 v41, v32, v38
	v_min_u32_e32 v42, v40, v36
	v_min_u32_e32 v43, v34, v33
	v_min_u32_e32 v44, v35, v37
	v_min_u32_e32 v45, v29, v28
	v_min_u32_e32 v46, v30, v26
	v_min_u32_e32 v47, v24, v25
	v_max3_u32 v7, v7, v15, v47
	v_max3_u32 v3, v3, v24, v25
	v_max3_u32 v12, v12, v13, v46
	v_max3_u32 v13, v17, v30, v26
	v_max3_u32 v11, v16, v11, v45
	v_max3_u32 v15, v18, v29, v28
	v_max3_u32 v8, v9, v8, v44
	v_max3_u32 v9, v19, v35, v37
	v_max3_u32 v10, v10, v14, v43
	v_max3_u32 v14, v20, v34, v33
	v_max3_u32 v4, v5, v4, v42
	v_max3_u32 v5, v21, v40, v36
	v_max3_u32 v2, v6, v2, v41
	v_max3_u32 v6, v22, v32, v38
	v_max3_u32 v0, v0, v1, v27
	v_max3_u32 v1, v23, v31, v39
	v_max_u32_e32 v16, v7, v10
	v_min_u32_e32 v7, v7, v10
	v_max_u32_e32 v10, v3, v14
	v_min_u32_e32 v3, v3, v14
	v_max_u32_e32 v14, v12, v4
	v_min_u32_e32 v4, v12, v4
	v_max_u32_e32 v12, v13, v5
	v_min_u32_e32 v5, v13, v5
	v_max_u32_e32 v13, v11, v2
	v_min_u32_e32 v2, v11, v2
	v_max_u32_e32 v11, v15, v6
	v_min_u32_e32 v6, v15, v6
	v_max_u32_e32 v15, v8, v0
	v_min_u32_e32 v0, v8, v0
	v_max_u32_e32 v8, v9, v1
	v_min_u32_e32 v1, v9, v1
	v_max_u32_e32 v9, v16, v13
	v_min_u32_e32 v13, v16, v13
	v_max_u32_e32 v16, v10, v11
	v_min_u32_e32 v10, v10, v11
	v_max_u32_e32 v11, v14, v15
	v_min_u32_e32 v14, v14, v15
	v_max_u32_e32 v15, v12, v8
	v_min_u32_e32 v8, v12, v8
	v_max_u32_e32 v12, v7, v2
	v_min_u32_e32 v2, v7, v2
	v_max_u32_e32 v7, v3, v6
	v_min_u32_e32 v3, v3, v6
	v_max_u32_e32 v6, v4, v0
	v_min_u32_e32 v0, v4, v0
	v_max_u32_e32 v4, v5, v1
	v_min_u32_e32 v1, v5, v1
	v_max_u32_e32 v5, v9, v11
	v_min_u32_e32 v9, v9, v11
	v_max_u32_e32 v11, v16, v15
	v_min_u32_e32 v15, v16, v15
	v_max_u32_e32 v16, v13, v14
	v_min_u32_e32 v13, v13, v14
	v_max_u32_e32 v14, v10, v8
	v_min_u32_e32 v8, v10, v8
	v_max_u32_e32 v10, v12, v6
	v_max_u32_e32 v17, v7, v4
	v_min_u32_e32 v18, v7, v4
	v_max_u32_e32 v19, v2, v0
	v_min_u32_e32 v20, v2, v0
	v_max_u32_e32 v21, v3, v1
	v_min_u32_e32 v22, v3, v1
	v_max_u32_e32 v0, v5, v11
	v_min_u32_e32 v1, v5, v11
	v_max_u32_e32 v4, v16, v14
	v_min_u32_e32 v5, v16, v14
	v_or_b32_e32 v16, s60, v128
	v_min_u32_e32 v12, v12, v6
	v_max_u32_e32 v2, v9, v15
	v_min_u32_e32 v3, v9, v15
	v_max_u32_e32 v6, v13, v8
	v_min_u32_e32 v7, v13, v8
	v_max_u32_e32 v8, v10, v17
	v_min_u32_e32 v9, v10, v17
	v_ashrrev_i32_e32 v17, 31, v16
	v_max_u32_e32 v10, v12, v18
	v_min_u32_e32 v11, v12, v18
	v_lshlrev_b64 v[16:17], 10, v[16:17]
	v_lshlrev_b32_e32 v18, 4, v130
	v_max_u32_e32 v12, v19, v21
	v_min_u32_e32 v13, v19, v21
	v_lshl_add_u64 v[16:17], s[12:13], 0, v[16:17]
	v_ashrrev_i32_e32 v19, 31, v18
	v_lshl_add_u64 v[16:17], v[18:19], 2, v[16:17]
	v_max_u32_e32 v14, v20, v22
	v_min_u32_e32 v15, v20, v22
	v_and_b32_e32 v238, 3, v128
	v_lshl_add_u32 v239, v128, 8, v131
	v_lshl_add_u32 v239, v238, 6, v239
	ds_write_b128 v239, v[0:3]
	ds_write_b128 v239, v[4:7] offset:16
	ds_write_b128 v239, v[8:11] offset:32
	ds_write_b128 v239, v[12:15] offset:48
	v_bfe_u32 v242, v128, 2, 4
	v_and_or_b32 v242, v128, 64, v242
	v_and_b32_e32 v243, 3, v242
	v_lshlrev_b32_e32 v243, 6, v243
	v_lshl_add_u32 v243, v238, 4, v243
	v_lshl_add_u32 v243, v242, 8, v243
	v_add_u32_e32 v243, v131, v243
	ds_read_b128 v[20:23], v243
	ds_read_b128 v[24:27], v243 offset:4096
	ds_read_b128 v[28:31], v243 offset:8192
	ds_read_b128 v[32:35], v243 offset:12288
	v_or_b32_e32 v244, s60, v242
	v_ashrrev_i32_e32 v245, 31, v244
	v_lshlrev_b64 v[244:245], 10, v[244:245]
	v_lshl_add_u64 v[244:245], s[12:13], 0, v[244:245]
	v_lshl_add_u64 v[244:245], v[18:19], 2, v[244:245]
	v_lshlrev_b32_e32 v246, 4, v238
	v_mov_b32_e32 v247, 0
	v_lshl_add_u64 v[244:245], v[244:245], 0, v[246:247]
	v_mov_b32_e32 v246, 0x4000
	s_waitcnt lgkmcnt(3)
	global_store_dwordx4 v[244:245], v[20:23], off
	v_lshl_add_u64 v[244:245], v[244:245], 0, v[246:247]
	s_waitcnt lgkmcnt(2)
	global_store_dwordx4 v[244:245], v[24:27], off
	v_lshl_add_u64 v[244:245], v[244:245], 0, v[246:247]
	s_waitcnt lgkmcnt(1)
	global_store_dwordx4 v[244:245], v[28:31], off
	v_lshl_add_u64 v[244:245], v[244:245], 0, v[246:247]
	s_waitcnt lgkmcnt(0)
	global_store_dwordx4 v[244:245], v[32:35], off
.LBB0_867:
	s_or_b64 exec, exec, s[62:63]
	v_mov_b32_e32 v0, v176
	s_barrier
	v_cvt_pk_bf16_f32 v124, v124, v125
	v_cvt_pk_bf16_f32 v125, v126, v127
	v_cvt_pk_bf16_f32 v116, v116, v117
	v_cvt_pk_bf16_f32 v117, v118, v119
	v_cvt_pk_bf16_f32 v120, v120, v121
	v_cvt_pk_bf16_f32 v121, v122, v123
	v_cvt_pk_bf16_f32 v112, v112, v113
	v_cvt_pk_bf16_f32 v113, v114, v115
	v_cvt_pk_bf16_f32 v108, v108, v109
	v_cvt_pk_bf16_f32 v109, v110, v111
	v_cvt_pk_bf16_f32 v96, v96, v97
	v_cvt_pk_bf16_f32 v97, v98, v99
	v_cvt_pk_bf16_f32 v104, v104, v105
	v_cvt_pk_bf16_f32 v105, v106, v107
	v_cvt_pk_bf16_f32 v88, v88, v89
	v_cvt_pk_bf16_f32 v89, v90, v91
	v_cvt_pk_bf16_f32 v100, v100, v101
	v_cvt_pk_bf16_f32 v101, v102, v103
	v_cvt_pk_bf16_f32 v92, v92, v93
	v_cvt_pk_bf16_f32 v93, v94, v95
	v_cvt_pk_bf16_f32 v84, v84, v85
	v_cvt_pk_bf16_f32 v85, v86, v87
	v_cvt_pk_bf16_f32 v80, v80, v81
	v_cvt_pk_bf16_f32 v81, v82, v83
	v_cvt_pk_bf16_f32 v76, v76, v77
	v_cvt_pk_bf16_f32 v77, v78, v79
	v_cvt_pk_bf16_f32 v72, v72, v73
	v_cvt_pk_bf16_f32 v73, v74, v75
	v_cvt_pk_bf16_f32 v68, v68, v69
	v_cvt_pk_bf16_f32 v69, v70, v71
	v_cvt_pk_bf16_f32 v64, v64, v65
	v_cvt_pk_bf16_f32 v65, v66, v67
	v_and_b32_e32 v1, 15, v0
	v_lshrrev_b32_e32 v2, 1, v0
	v_and_or_b32 v2, v2, s81, v1
	v_ashrrev_i32_e32 v1, 2, v0
	v_lshrrev_b32_e32 v0, 2, v0
	v_and_b32_e32 v0, 12, v0
	v_and_or_b32 v3, v1, s82, v0
	v_mul_u32_u24_e32 v2, 0x110, v2
	v_lshl_add_u32 v6, v3, 1, v2
	v_add_u32_e32 v7, 0x8000, v6
	ds_write2_b64 v7, v[124:125], v[116:117] offset1:4
	v_add_u32_e32 v8, 0x9000, v6
	ds_write2_b64 v8, v[120:121], v[112:113] offset0:32 offset1:36
	ds_write2_b64 v7, v[108:109], v[96:97] offset0:8 offset1:12
	ds_write2_b64 v8, v[104:105], v[88:89] offset0:40 offset1:44
	v_add_u32_e32 v2, 0x1a000, v6
	ds_write_b64 v2, v[100:101]
	ds_write_b64 v2, v[92:93] offset:4352
	v_add_u32_e32 v2, 0x1a020, v6
	ds_write_b64 v2, v[84:85]
	ds_write_b64 v2, v[80:81] offset:4352
	v_add_u32_e32 v2, 0x1a040, v6
	ds_write_b64 v2, v[76:77]
	ds_write_b64 v2, v[72:73] offset:4352
	v_add_u32_e32 v2, 0x1a060, v6
	ds_write_b64 v2, v[68:69]
	v_mov_b32_e32 v71, v176
	ds_write_b64 v2, v[64:65] offset:4352
	s_nop 0
	v_ashrrev_i32_e32 v67, 8, v71
	v_add_u32_e32 v64, s59, v67
	v_bfe_u32 v69, v71, 7, 1
	v_ashrrev_i32_e32 v65, 31, v64
	v_and_b32_e32 v2, 31, v71
	v_lshlrev_b64 v[0:1], 7, v[64:65]
	v_lshlrev_b32_e32 v70, 6, v69
	v_or3_b32 v0, v0, v70, v2
	v_bfe_u32 v68, v71, 5, 1
	v_lshlrev_b64 v[0:1], 8, v[0:1]
	v_lshl_add_u64 v[0:1], s[4:5], 0, v[0:1]
	v_lshlrev_b32_e32 v128, 4, v68
	v_lshl_add_u64 v[8:9], v[0:1], 0, v[128:129]
	global_load_dwordx4 v[0:3], v[8:9], off
	v_add_co_u32_e32 v10, vcc, s76, v8
	v_mul_i32_i24_e32 v66, 0x12000, v67
	s_nop 0
	v_addc_co_u32_e32 v11, vcc, 0, v9, vcc
	global_load_dwordx4 v[4:7], v[10:11], off
	global_load_dwordx4 v[72:75], v[8:9], off offset:32
	global_load_dwordx4 v[76:79], v[10:11], off offset:32
	global_load_dwordx4 v[80:83], v[8:9], off offset:64
	global_load_dwordx4 v[84:87], v[8:9], off offset:96
	global_load_dwordx4 v[88:91], v[10:11], off offset:64
	global_load_dwordx4 v[92:95], v[10:11], off offset:96
	global_load_dwordx4 v[96:99], v[8:9], off offset:128
	global_load_dwordx4 v[100:103], v[8:9], off offset:160
	global_load_dwordx4 v[104:107], v[10:11], off offset:128
	global_load_dwordx4 v[108:111], v[10:11], off offset:160
	global_load_dwordx4 v[112:115], v[8:9], off offset:192
	global_load_dwordx4 v[116:119], v[8:9], off offset:224
	global_load_dwordx4 v[120:123], v[10:11], off offset:192
	global_load_dwordx4 v[124:127], v[10:11], off offset:224
	v_and_b32_e32 v8, 0x5f, v71
	v_mul_u32_u24_e32 v8, 0x110, v8
	v_add3_u32 v65, v66, v8, v128
	s_waitcnt lgkmcnt(0)
	s_barrier
	ds_read_b128 v[8:11], v65 offset:32768
	ds_read_b128 v[130:133], v65 offset:32800
	s_waitcnt vmcnt(15) lgkmcnt(1)
	v_mfma_f32_32x32x16_bf16 v[32:47], v[0:3], v[8:11], 0
	ds_read_b128 v[12:15], v65 offset:41472
	ds_read_b128 v[136:139], v65 offset:41504
	v_lshlrev_b32_e32 v69, 1, v69
	s_waitcnt vmcnt(14)
	v_mfma_f32_32x32x16_bf16 v[48:63], v[4:7], v[8:11], 0
	s_waitcnt lgkmcnt(1)
	v_mfma_f32_32x32x16_bf16 v[16:31], v[0:3], v[12:15], 0
	v_mfma_f32_32x32x16_bf16 v[0:15], v[4:7], v[12:15], 0
	s_waitcnt vmcnt(13)
	v_mfma_f32_32x32x16_bf16 v[32:47], v[72:75], v[130:133], v[32:47]
	s_waitcnt vmcnt(12)
	v_mfma_f32_32x32x16_bf16 v[48:63], v[76:79], v[130:133], v[48:63]
	s_waitcnt lgkmcnt(0)
	v_mfma_f32_32x32x16_bf16 v[16:31], v[72:75], v[136:139], v[16:31]
	v_mfma_f32_32x32x16_bf16 v[0:15], v[76:79], v[136:139], v[0:15]
	ds_read_b128 v[72:75], v65 offset:32832
	ds_read_b128 v[76:79], v65 offset:32864
	ds_read_b128 v[130:133], v65 offset:41536
	ds_read_b128 v[136:139], v65 offset:41568
	s_waitcnt vmcnt(11) lgkmcnt(3)
	v_mfma_f32_32x32x16_bf16 v[32:47], v[80:83], v[72:75], v[32:47]
	s_waitcnt vmcnt(9)
	v_mfma_f32_32x32x16_bf16 v[48:63], v[88:91], v[72:75], v[48:63]
	s_waitcnt lgkmcnt(1)
	v_mfma_f32_32x32x16_bf16 v[16:31], v[80:83], v[130:133], v[16:31]
	v_mfma_f32_32x32x16_bf16 v[0:15], v[88:91], v[130:133], v[0:15]
	v_mfma_f32_32x32x16_bf16 v[32:47], v[84:87], v[76:79], v[32:47]
	s_waitcnt vmcnt(8)
	v_mfma_f32_32x32x16_bf16 v[48:63], v[92:95], v[76:79], v[48:63]
	ds_read_b128 v[72:75], v65 offset:32896
	ds_read_b128 v[76:79], v65 offset:32928
	s_waitcnt lgkmcnt(2)
	v_mfma_f32_32x32x16_bf16 v[16:31], v[84:87], v[136:139], v[16:31]
	ds_read_b128 v[80:83], v65 offset:41600
	ds_read_b128 v[84:87], v65 offset:41632
	v_mfma_f32_32x32x16_bf16 v[0:15], v[92:95], v[136:139], v[0:15]
	s_waitcnt vmcnt(7) lgkmcnt(3)
	v_mfma_f32_32x32x16_bf16 v[32:47], v[96:99], v[72:75], v[32:47]
	s_waitcnt vmcnt(5)
	v_mfma_f32_32x32x16_bf16 v[48:63], v[104:107], v[72:75], v[48:63]
	s_waitcnt lgkmcnt(1)
	v_mfma_f32_32x32x16_bf16 v[16:31], v[96:99], v[80:83], v[16:31]
	v_mfma_f32_32x32x16_bf16 v[0:15], v[104:107], v[80:83], v[0:15]
	v_mfma_f32_32x32x16_bf16 v[32:47], v[100:103], v[76:79], v[32:47]
	s_waitcnt vmcnt(4)
	v_mfma_f32_32x32x16_bf16 v[48:63], v[108:111], v[76:79], v[48:63]
	ds_read_b128 v[72:75], v65 offset:32960
	ds_read_b128 v[76:79], v65 offset:32992
	s_waitcnt lgkmcnt(2)
	v_mfma_f32_32x32x16_bf16 v[16:31], v[100:103], v[84:87], v[16:31]
	v_mfma_f32_32x32x16_bf16 v[0:15], v[108:111], v[84:87], v[0:15]
	ds_read_b128 v[80:83], v65 offset:41664
	ds_read_b128 v[84:87], v65 offset:41696
	v_and_b32_e32 v65, 0xff, v71
	v_cmp_gt_u32_e32 vcc, s77, v65
	s_waitcnt vmcnt(3) lgkmcnt(3)
	v_mfma_f32_32x32x16_bf16 v[32:47], v[112:115], v[72:75], v[32:47]
	s_waitcnt vmcnt(1)
	v_mfma_f32_32x32x16_bf16 v[48:63], v[120:123], v[72:75], v[48:63]
	v_lshlrev_b32_e32 v72, 2, v68
	s_waitcnt lgkmcnt(1)
	v_mfma_f32_32x32x16_bf16 v[16:31], v[112:115], v[80:83], v[16:31]
	v_mfma_f32_32x32x16_bf16 v[0:15], v[120:123], v[80:83], v[0:15]
	v_mfma_f32_32x32x16_bf16 v[32:47], v[116:119], v[76:79], v[32:47]
	s_waitcnt vmcnt(0)
	v_mfma_f32_32x32x16_bf16 v[48:63], v[124:127], v[76:79], v[48:63]
	s_nop 9
	v_ashrrev_i32_e32 v73, 31, v32
	v_ashrrev_i32_e32 v74, 31, v33
	v_ashrrev_i32_e32 v75, 31, v34
	v_ashrrev_i32_e32 v76, 31, v35
	v_ashrrev_i32_e32 v77, 31, v36
	v_ashrrev_i32_e32 v78, 31, v37
	v_ashrrev_i32_e32 v79, 31, v38
	s_waitcnt lgkmcnt(0)
	v_mfma_f32_32x32x16_bf16 v[16:31], v[116:119], v[84:87], v[16:31]
	v_ashrrev_i32_e32 v80, 31, v39
	v_ashrrev_i32_e32 v81, 31, v40
	v_ashrrev_i32_e32 v82, 31, v41
	v_ashrrev_i32_e32 v83, 31, v42
	v_ashrrev_i32_e32 v88, 31, v47
	v_or_b32_e32 v73, 0x80000000, v73
	v_or_b32_e32 v74, 0x80000000, v74
	v_mfma_f32_32x32x16_bf16 v[0:15], v[124:127], v[84:87], v[0:15]
	v_ashrrev_i32_e32 v84, 31, v43
	v_ashrrev_i32_e32 v85, 31, v44
	v_ashrrev_i32_e32 v86, 31, v45
	v_ashrrev_i32_e32 v87, 31, v46
	v_or_b32_e32 v75, 0x80000000, v75
	v_or_b32_e32 v76, 0x80000000, v76
	v_or_b32_e32 v77, 0x80000000, v77
	v_or_b32_e32 v78, 0x80000000, v78
	v_or_b32_e32 v79, 0x80000000, v79
	v_or_b32_e32 v80, 0x80000000, v80
	v_or_b32_e32 v81, 0x80000000, v81
	v_or_b32_e32 v82, 0x80000000, v82
	v_or_b32_e32 v83, 0x80000000, v83
	v_or_b32_e32 v84, 0x80000000, v84
	v_or_b32_e32 v85, 0x80000000, v85
	v_or_b32_e32 v86, 0x80000000, v86
	v_or_b32_e32 v87, 0x80000000, v87
	v_or_b32_e32 v88, 0x80000000, v88
	v_bitop3_b32 v32, v73, s86, v32 bitop3:0x48
	v_ashrrev_i32_e32 v73, 31, v48
	v_bitop3_b32 v33, v74, s86, v33 bitop3:0x48
	v_ashrrev_i32_e32 v74, 31, v49
	v_bitop3_b32 v34, v75, s86, v34 bitop3:0x48
	v_ashrrev_i32_e32 v75, 31, v50
	v_bitop3_b32 v35, v76, s86, v35 bitop3:0x48
	v_ashrrev_i32_e32 v76, 31, v51
	v_bitop3_b32 v36, v77, s86, v36 bitop3:0x48
	v_ashrrev_i32_e32 v77, 31, v52
	v_bitop3_b32 v37, v78, s86, v37 bitop3:0x48
	v_ashrrev_i32_e32 v78, 31, v53
	v_bitop3_b32 v38, v79, s86, v38 bitop3:0x48
	v_ashrrev_i32_e32 v79, 31, v54
	v_bitop3_b32 v39, v80, s86, v39 bitop3:0x48
	v_ashrrev_i32_e32 v80, 31, v55
	v_bitop3_b32 v40, v81, s86, v40 bitop3:0x48
	v_ashrrev_i32_e32 v81, 31, v56
	v_bitop3_b32 v41, v82, s86, v41 bitop3:0x48
	v_ashrrev_i32_e32 v82, 31, v57
	v_bitop3_b32 v42, v83, s86, v42 bitop3:0x48
	v_ashrrev_i32_e32 v83, 31, v58
	v_bitop3_b32 v43, v84, s86, v43 bitop3:0x48
	v_ashrrev_i32_e32 v84, 31, v59
	v_bitop3_b32 v44, v85, s86, v44 bitop3:0x48
	v_ashrrev_i32_e32 v85, 31, v60
	v_bitop3_b32 v45, v86, s86, v45 bitop3:0x48
	v_ashrrev_i32_e32 v86, 31, v61
	v_bitop3_b32 v46, v87, s86, v46 bitop3:0x48
	v_ashrrev_i32_e32 v87, 31, v62
	v_bitop3_b32 v47, v88, s86, v47 bitop3:0x48
	v_ashrrev_i32_e32 v88, 31, v63
	v_bitop3_b32 v48, v73, v48, s85 bitop3:0x36
	v_or_b32_e32 v73, 1, v72
	v_bitop3_b32 v49, v74, v49, s85 bitop3:0x36
	v_or_b32_e32 v74, 2, v72
	v_bitop3_b32 v50, v75, v50, s85 bitop3:0x36
	v_or_b32_e32 v75, 3, v72
	v_bitop3_b32 v51, v76, v51, s85 bitop3:0x36
	v_or_b32_e32 v76, 8, v72
	v_bitop3_b32 v52, v77, v52, s85 bitop3:0x36
	v_or_b32_e32 v77, 9, v72
	v_bitop3_b32 v53, v78, v53, s85 bitop3:0x36
	v_or_b32_e32 v78, 10, v72
	v_bitop3_b32 v54, v79, v54, s85 bitop3:0x36
	v_or_b32_e32 v79, 11, v72
	v_bitop3_b32 v55, v80, v55, s85 bitop3:0x36
	v_or_b32_e32 v80, 16, v72
	v_bitop3_b32 v56, v81, v56, s85 bitop3:0x36
	v_or_b32_e32 v81, 17, v72
	v_bitop3_b32 v57, v82, v57, s85 bitop3:0x36
	v_or_b32_e32 v82, 18, v72
	v_bitop3_b32 v58, v83, v58, s85 bitop3:0x36
	v_or_b32_e32 v83, 19, v72
	v_bitop3_b32 v59, v84, v59, s85 bitop3:0x36
	v_or_b32_e32 v84, 24, v72
	v_bitop3_b32 v60, v85, v60, s85 bitop3:0x36
	v_or_b32_e32 v85, 25, v72
	v_bitop3_b32 v61, v86, v61, s85 bitop3:0x36
	v_or_b32_e32 v86, 26, v72
	v_bitop3_b32 v62, v87, v62, s85 bitop3:0x36
	v_or_b32_e32 v87, 27, v72
	v_bitop3_b32 v63, v88, v63, s85 bitop3:0x36
	v_and_or_b32 v48, v48, s86, v72
	v_and_or_b32 v49, v49, s86, v73
	v_and_or_b32 v50, v50, s86, v74
	v_and_or_b32 v51, v51, s86, v75
	v_and_or_b32 v52, v52, s86, v76
	v_and_or_b32 v53, v53, s86, v77
	v_and_or_b32 v54, v54, s86, v78
	v_and_or_b32 v55, v55, s86, v79
	v_and_or_b32 v56, v56, s86, v80
	v_and_or_b32 v57, v57, s86, v81
	v_and_or_b32 v58, v58, s86, v82
	v_and_or_b32 v59, v59, s86, v83
	v_and_or_b32 v60, v60, s86, v84
	v_and_or_b32 v61, v61, s86, v85
	v_and_or_b32 v62, v62, s86, v86
	v_and_or_b32 v63, v63, s86, v87
	v_or3_b32 v32, v70, v32, v72
	v_or3_b32 v48, v48, v70, 32
	v_or3_b32 v33, v70, v33, v73
	v_or3_b32 v49, v49, v70, 32
	v_or3_b32 v34, v70, v34, v74
	v_or3_b32 v50, v50, v70, 32
	v_or3_b32 v35, v70, v35, v75
	v_or3_b32 v51, v51, v70, 32
	v_or3_b32 v36, v70, v36, v76
	v_or3_b32 v52, v52, v70, 32
	v_or3_b32 v37, v70, v37, v77
	v_or3_b32 v53, v53, v70, 32
	v_or3_b32 v38, v70, v38, v78
	v_or3_b32 v54, v54, v70, 32
	v_or3_b32 v39, v70, v39, v79
	v_or3_b32 v55, v55, v70, 32
	v_or3_b32 v40, v70, v40, v80
	v_or3_b32 v56, v56, v70, 32
	v_or3_b32 v41, v70, v41, v81
	v_or3_b32 v57, v57, v70, 32
	v_or3_b32 v42, v70, v42, v82
	v_or3_b32 v58, v58, v70, 32
	v_or3_b32 v43, v70, v43, v83
	v_or3_b32 v59, v59, v70, 32
	v_or3_b32 v44, v70, v44, v84
	v_or3_b32 v60, v60, v70, 32
	v_or3_b32 v45, v70, v45, v85
	v_or3_b32 v61, v61, v70, 32
	v_or3_b32 v46, v70, v46, v86
	v_or3_b32 v62, v62, v70, 32
	v_or3_b32 v47, v70, v47, v87
	v_or3_b32 v63, v63, v70, 32
	v_max_u32_e32 v88, v32, v45
	v_min_u32_e32 v32, v32, v45
	v_max_u32_e32 v45, v33, v44
	v_min_u32_e32 v33, v33, v44
	v_max_u32_e32 v44, v34, v47
	v_min_u32_e32 v34, v34, v47
	v_max_u32_e32 v47, v35, v46
	v_min_u32_e32 v35, v35, v46
	v_max_u32_e32 v46, v36, v40
	v_min_u32_e32 v36, v36, v40
	v_max_u32_e32 v40, v37, v38
	v_min_u32_e32 v37, v37, v38
	v_max_u32_e32 v38, v39, v43
	v_min_u32_e32 v39, v39, v43
	v_max_u32_e32 v43, v41, v42
	v_min_u32_e32 v41, v41, v42
	v_max_u32_e32 v96, v48, v61
	v_min_u32_e32 v48, v48, v61
	v_max_u32_e32 v61, v49, v60
	v_min_u32_e32 v49, v49, v60
	v_max_u32_e32 v60, v50, v63
	v_min_u32_e32 v50, v50, v63
	v_max_u32_e32 v63, v51, v62
	v_min_u32_e32 v51, v51, v62
	v_max_u32_e32 v62, v52, v56
	v_min_u32_e32 v52, v52, v56
	v_max_u32_e32 v56, v53, v54
	v_min_u32_e32 v53, v53, v54
	v_max_u32_e32 v54, v55, v59
	v_min_u32_e32 v55, v55, v59
	v_max_u32_e32 v59, v57, v58
	v_min_u32_e32 v57, v57, v58
	v_max_u32_e32 v42, v88, v40
	v_min_u32_e32 v40, v88, v40
	v_max_u32_e32 v88, v45, v38
	v_min_u32_e32 v38, v45, v38
	v_max_u32_e32 v45, v44, v43
	v_min_u32_e32 v43, v44, v43
	v_max_u32_e32 v44, v47, v46
	v_min_u32_e32 v46, v47, v46
	v_max_u32_e32 v47, v37, v32
	v_min_u32_e32 v32, v37, v32
	v_max_u32_e32 v37, v36, v35
	v_min_u32_e32 v35, v36, v35
	v_max_u32_e32 v36, v41, v34
	v_min_u32_e32 v34, v41, v34
	v_max_u32_e32 v41, v39, v33
	v_min_u32_e32 v33, v39, v33
	v_max_u32_e32 v58, v96, v56
	v_min_u32_e32 v56, v96, v56
	v_max_u32_e32 v96, v61, v54
	v_min_u32_e32 v54, v61, v54
	v_max_u32_e32 v61, v60, v59
	v_min_u32_e32 v59, v60, v59
	v_max_u32_e32 v60, v63, v62
	v_min_u32_e32 v62, v63, v62
	v_max_u32_e32 v63, v53, v48
	v_min_u32_e32 v48, v53, v48
	v_max_u32_e32 v53, v52, v51
	v_min_u32_e32 v51, v52, v51
	v_max_u32_e32 v52, v57, v50
	v_min_u32_e32 v50, v57, v50
	v_max_u32_e32 v57, v55, v49
	v_min_u32_e32 v49, v55, v49
	v_max_u32_e32 v39, v42, v88
	v_min_u32_e32 v42, v42, v88
	v_max_u32_e32 v88, v45, v44
	v_min_u32_e32 v44, v45, v44
	v_max_u32_e32 v45, v46, v40
	v_min_u32_e32 v40, v46, v40
	v_max_u32_e32 v46, v47, v37
	v_min_u32_e32 v37, v47, v37
	v_max_u32_e32 v47, v38, v43
	v_min_u32_e32 v38, v38, v43
	v_max_u32_e32 v43, v36, v41
	v_min_u32_e32 v36, v36, v41
	v_max_u32_e32 v41, v33, v32
	v_min_u32_e32 v32, v33, v32
	v_max_u32_e32 v33, v35, v34
	v_min_u32_e32 v34, v35, v34
	v_max_u32_e32 v55, v58, v96
	v_min_u32_e32 v58, v58, v96
	v_max_u32_e32 v96, v61, v60
	v_min_u32_e32 v60, v61, v60
	v_max_u32_e32 v61, v62, v56
	v_min_u32_e32 v56, v62, v56
	v_max_u32_e32 v62, v63, v53
	v_min_u32_e32 v53, v63, v53
	v_max_u32_e32 v63, v54, v59
	v_min_u32_e32 v54, v54, v59
	v_max_u32_e32 v59, v52, v57
	v_min_u32_e32 v52, v52, v57
	v_max_u32_e32 v57, v49, v48
	v_min_u32_e32 v48, v49, v48
	v_max_u32_e32 v49, v51, v50
	v_min_u32_e32 v50, v51, v50
	v_min_u32_e32 v35, v39, v88
	v_max_u32_e32 v89, v42, v44
	v_min_u32_e32 v42, v42, v44
	v_max_u32_e32 v44, v45, v43
	v_min_u32_e32 v43, v45, v43
	v_max_u32_e32 v45, v40, v36
	v_min_u32_e32 v36, v40, v36
	v_max_u32_e32 v40, v46, v47
	v_min_u32_e32 v46, v46, v47
	v_max_u32_e32 v47, v37, v38
	v_min_u32_e32 v37, v37, v38
	v_max_u32_e32 v38, v41, v33
	v_min_u32_e32 v33, v41, v33
	v_max_u32_e32 v41, v32, v34
	v_min_u32_e32 v51, v55, v96
	v_max_u32_e32 v97, v58, v60
	v_min_u32_e32 v58, v58, v60
	v_max_u32_e32 v60, v61, v59
	v_min_u32_e32 v59, v61, v59
	v_max_u32_e32 v61, v56, v52
	v_min_u32_e32 v52, v56, v52
	v_max_u32_e32 v56, v62, v63
	v_min_u32_e32 v62, v62, v63
	v_max_u32_e32 v63, v53, v54
	v_min_u32_e32 v53, v53, v54
	v_max_u32_e32 v54, v57, v49
	v_min_u32_e32 v49, v57, v49
	v_max_u32_e32 v57, v48, v50
	v_min_u32_e32 v32, v32, v34
	v_max_u32_e32 v34, v89, v35
	v_min_u32_e32 v35, v89, v35
	v_max_u32_e32 v89, v42, v38
	v_min_u32_e32 v38, v42, v38
	v_max_u32_e32 v42, v44, v40
	v_min_u32_e32 v40, v44, v40
	v_max_u32_e32 v44, v45, v46
	v_min_u32_e32 v45, v45, v46
	v_max_u32_e32 v46, v47, v43
	v_min_u32_e32 v43, v47, v43
	v_max_u32_e32 v47, v37, v36
	v_min_u32_e32 v36, v37, v36
	v_max_u32_e32 v37, v41, v33
	v_min_u32_e32 v48, v48, v50
	v_max_u32_e32 v50, v97, v51
	v_min_u32_e32 v51, v97, v51
	v_max_u32_e32 v97, v58, v54
	v_min_u32_e32 v54, v58, v54
	v_max_u32_e32 v58, v60, v56
	v_min_u32_e32 v56, v60, v56
	v_max_u32_e32 v60, v61, v62
	v_min_u32_e32 v61, v61, v62
	v_max_u32_e32 v62, v63, v59
	v_min_u32_e32 v59, v63, v59
	v_max_u32_e32 v63, v53, v52
	v_min_u32_e32 v52, v53, v52
	v_max_u32_e32 v53, v57, v49
	v_min_u32_e32 v33, v41, v33
	v_max_u32_e32 v90, v35, v40
	v_min_u32_e32 v35, v35, v40
	v_max_u32_e32 v40, v44, v46
	v_min_u32_e32 v44, v44, v46
	v_max_u32_e32 v46, v45, v43
	v_min_u32_e32 v43, v45, v43
	v_max_u32_e32 v45, v47, v37
	v_min_u32_e32 v49, v57, v49
	v_max_u32_e32 v98, v51, v56
	v_min_u32_e32 v51, v51, v56
	v_max_u32_e32 v56, v60, v62
	v_min_u32_e32 v60, v60, v62
	v_max_u32_e32 v62, v61, v59
	v_min_u32_e32 v59, v61, v59
	v_max_u32_e32 v61, v63, v53
	v_min_u32_e32 v37, v47, v37
	v_max_u32_e32 v47, v36, v33
	v_max_u32_e32 v91, v89, v35
	v_min_u32_e32 v35, v89, v35
	v_max_u32_e32 v89, v45, v38
	v_min_u32_e32 v38, v45, v38
	v_min_u32_e32 v53, v63, v53
	v_max_u32_e32 v63, v52, v49
	v_max_u32_e32 v99, v97, v51
	v_min_u32_e32 v51, v97, v51
	v_max_u32_e32 v97, v61, v54
	v_min_u32_e32 v54, v61, v54
	v_min_u32_e32 v41, v34, v42
	v_max_u32_e32 v45, v47, v37
	v_min_u32_e32 v37, v47, v37
	v_max_u32_e32 v47, v91, v40
	v_min_u32_e32 v40, v91, v40
	v_max_u32_e32 v91, v35, v44
	v_min_u32_e32 v35, v35, v44
	v_max_u32_e32 v44, v46, v89
	v_min_u32_e32 v46, v46, v89
	v_max_u32_e32 v89, v43, v38
	v_min_u32_e32 v57, v50, v58
	v_max_u32_e32 v61, v63, v53
	v_min_u32_e32 v53, v63, v53
	v_max_u32_e32 v63, v99, v56
	v_min_u32_e32 v56, v99, v56
	v_max_u32_e32 v99, v51, v60
	v_min_u32_e32 v51, v51, v60
	v_max_u32_e32 v60, v62, v97
	v_min_u32_e32 v62, v62, v97
	v_max_u32_e32 v97, v59, v54
	v_min_u32_e32 v33, v36, v33
	v_min_u32_e32 v36, v90, v41
	v_min_u32_e32 v38, v43, v38
	v_min_u32_e32 v92, v40, v91
	v_max_u32_e32 v93, v44, v35
	v_min_u32_e32 v35, v44, v35
	v_max_u32_e32 v44, v46, v89
	v_min_u32_e32 v49, v52, v49
	v_min_u32_e32 v52, v98, v57
	v_min_u32_e32 v54, v59, v54
	v_min_u32_e32 v100, v56, v99
	v_max_u32_e32 v101, v60, v51
	v_min_u32_e32 v51, v60, v51
	v_max_u32_e32 v60, v62, v97
	v_min_u32_e32 v43, v47, v36
	v_min_u32_e32 v46, v46, v89
	v_min_u32_e32 v89, v45, v38
	v_min_u32_e32 v94, v92, v93
	v_min_u32_e32 v95, v35, v44
	v_min_u32_e32 v59, v63, v52
	v_min_u32_e32 v62, v62, v97
	v_min_u32_e32 v97, v61, v54
	v_min_u32_e32 v102, v100, v101
	v_min_u32_e32 v103, v51, v60
	v_max3_u32 v39, v39, v88, v48
	v_max3_u32 v34, v34, v42, v49
	v_max3_u32 v41, v90, v41, v53
	v_max3_u32 v36, v47, v36, v97
	v_max3_u32 v42, v43, v61, v54
	v_max3_u32 v40, v40, v91, v62
	v_max3_u32 v43, v92, v93, v103
	v_max3_u32 v47, v94, v51, v60
	v_max3_u32 v35, v35, v44, v102
	v_max3_u32 v44, v95, v100, v101
	v_max3_u32 v46, v46, v56, v99
	v_max3_u32 v38, v45, v38, v59
	v_max3_u32 v45, v89, v63, v52
	v_max3_u32 v37, v37, v98, v57
	v_max3_u32 v33, v33, v50, v58
	v_max3_u32 v32, v32, v55, v96
	v_max_u32_e32 v48, v39, v35
	v_min_u32_e32 v35, v39, v35
	v_max_u32_e32 v39, v34, v44
	v_min_u32_e32 v34, v34, v44
	v_max_u32_e32 v44, v41, v46
	v_min_u32_e32 v41, v41, v46
	v_max_u32_e32 v46, v36, v38
	v_min_u32_e32 v36, v36, v38
	v_max_u32_e32 v38, v42, v45
	v_min_u32_e32 v42, v42, v45
	v_max_u32_e32 v45, v40, v37
	v_min_u32_e32 v37, v40, v37
	v_max_u32_e32 v40, v43, v33
	v_min_u32_e32 v33, v43, v33
	v_max_u32_e32 v43, v47, v32
	v_min_u32_e32 v32, v47, v32
	v_max_u32_e32 v47, v48, v38
	v_min_u32_e32 v38, v48, v38
	v_max_u32_e32 v48, v39, v45
	v_min_u32_e32 v39, v39, v45
	v_max_u32_e32 v45, v44, v40
	v_min_u32_e32 v40, v44, v40
	v_max_u32_e32 v44, v46, v43
	v_min_u32_e32 v43, v46, v43
	v_max_u32_e32 v46, v35, v42
	v_min_u32_e32 v35, v35, v42
	v_max_u32_e32 v42, v34, v37
	v_min_u32_e32 v34, v34, v37
	v_max_u32_e32 v37, v41, v33
	v_min_u32_e32 v33, v41, v33
	v_max_u32_e32 v41, v36, v32
	v_min_u32_e32 v32, v36, v32
	v_max_u32_e32 v36, v47, v45
	v_min_u32_e32 v45, v47, v45
	v_max_u32_e32 v47, v48, v44
	v_min_u32_e32 v44, v48, v44
	v_max_u32_e32 v48, v38, v40
	v_min_u32_e32 v40, v38, v40
	v_max_u32_e32 v38, v39, v43
	v_min_u32_e32 v39, v39, v43
	v_max_u32_e32 v43, v46, v37
	v_min_u32_e32 v46, v46, v37
	v_max_u32_e32 v51, v35, v33
	v_min_u32_e32 v52, v35, v33
	v_max_u32_e32 v53, v34, v32
	v_min_u32_e32 v54, v34, v32
	v_max_u32_e32 v32, v36, v47
	v_min_u32_e32 v33, v36, v47
	v_max_u32_e32 v36, v48, v38
	v_min_u32_e32 v37, v48, v38
	v_lshlrev_b32_e32 v48, 2, v71
	v_max_u32_e32 v49, v42, v41
	v_and_b32_e32 v48, 0x17c, v48
	v_min_u32_e32 v50, v42, v41
	v_max_u32_e32 v38, v40, v39
	v_min_u32_e32 v39, v40, v39
	v_max_u32_e32 v40, v43, v49
	v_min_u32_e32 v41, v43, v49
	v_or3_b32 v49, v69, v48, v68
	v_lshlrev_b32_e32 v49, 6, v49
	v_max_u32_e32 v34, v45, v44
	v_min_u32_e32 v35, v45, v44
	v_mad_i32_i24 v49, v67, s75, v49
	v_max_u32_e32 v42, v46, v50
	v_min_u32_e32 v43, v46, v50
	v_max_u32_e32 v44, v51, v53
	v_min_u32_e32 v45, v51, v53
	v_max_u32_e32 v46, v52, v54
	v_min_u32_e32 v47, v52, v54
	v_bfe_u32 v240, v49, 8, 4
	v_lshlrev_b32_e32 v240, 4, v240
	v_xor_b32_e32 v240, v49, v240
	ds_write_b128 v240, v[32:35]
	v_xor_b32_e32 v241, 16, v240
	ds_write_b128 v241, v[36:39]
	v_xor_b32_e32 v241, 32, v240
	ds_write_b128 v241, v[40:43]
	v_xor_b32_e32 v241, 48, v240
	ds_write_b128 v241, v[44:47]
	v_ashrrev_i32_e32 v32, 31, v16
	v_or_b32_e32 v32, 0x80000000, v32
	v_bitop3_b32 v16, v32, s86, v16 bitop3:0x48
	v_ashrrev_i32_e32 v32, 31, v0
	v_bitop3_b32 v0, v32, v0, s85 bitop3:0x36
	v_ashrrev_i32_e32 v32, 31, v17
	v_or_b32_e32 v32, 0x80000000, v32
	v_bitop3_b32 v17, v32, s86, v17 bitop3:0x48
	v_ashrrev_i32_e32 v32, 31, v1
	v_bitop3_b32 v1, v32, v1, s85 bitop3:0x36
	v_ashrrev_i32_e32 v32, 31, v18
	v_or_b32_e32 v32, 0x80000000, v32
	v_bitop3_b32 v18, v32, s86, v18 bitop3:0x48
	v_ashrrev_i32_e32 v32, 31, v2
	v_bitop3_b32 v2, v32, v2, s85 bitop3:0x36
	v_ashrrev_i32_e32 v32, 31, v19
	v_or_b32_e32 v32, 0x80000000, v32
	v_bitop3_b32 v19, v32, s86, v19 bitop3:0x48
	v_ashrrev_i32_e32 v32, 31, v3
	v_bitop3_b32 v3, v32, v3, s85 bitop3:0x36
	v_ashrrev_i32_e32 v32, 31, v20
	v_or_b32_e32 v32, 0x80000000, v32
	v_bitop3_b32 v20, v32, s86, v20 bitop3:0x48
	v_ashrrev_i32_e32 v32, 31, v4
	v_bitop3_b32 v4, v32, v4, s85 bitop3:0x36
	v_ashrrev_i32_e32 v32, 31, v21
	v_or_b32_e32 v32, 0x80000000, v32
	v_bitop3_b32 v21, v32, s86, v21 bitop3:0x48
	v_ashrrev_i32_e32 v32, 31, v5
	v_bitop3_b32 v5, v32, v5, s85 bitop3:0x36
	v_ashrrev_i32_e32 v32, 31, v22
	v_or_b32_e32 v32, 0x80000000, v32
	v_bitop3_b32 v22, v32, s86, v22 bitop3:0x48
	v_ashrrev_i32_e32 v32, 31, v6
	v_bitop3_b32 v6, v32, v6, s85 bitop3:0x36
	v_ashrrev_i32_e32 v32, 31, v23
	v_or_b32_e32 v32, 0x80000000, v32
	v_bitop3_b32 v23, v32, s86, v23 bitop3:0x48
	v_ashrrev_i32_e32 v32, 31, v7
	v_bitop3_b32 v7, v32, v7, s85 bitop3:0x36
	v_ashrrev_i32_e32 v32, 31, v24
	v_or_b32_e32 v32, 0x80000000, v32
	v_bitop3_b32 v24, v32, s86, v24 bitop3:0x48
	v_ashrrev_i32_e32 v32, 31, v8
	v_bitop3_b32 v8, v32, v8, s85 bitop3:0x36
	v_ashrrev_i32_e32 v32, 31, v25
	v_or_b32_e32 v32, 0x80000000, v32
	v_bitop3_b32 v25, v32, s86, v25 bitop3:0x48
	v_ashrrev_i32_e32 v32, 31, v9
	v_bitop3_b32 v9, v32, v9, s85 bitop3:0x36
	v_ashrrev_i32_e32 v32, 31, v26
	v_or_b32_e32 v32, 0x80000000, v32
	v_bitop3_b32 v26, v32, s86, v26 bitop3:0x48
	v_ashrrev_i32_e32 v32, 31, v10
	v_bitop3_b32 v10, v32, v10, s85 bitop3:0x36
	v_ashrrev_i32_e32 v32, 31, v27
	v_or_b32_e32 v32, 0x80000000, v32
	v_bitop3_b32 v27, v32, s86, v27 bitop3:0x48
	v_ashrrev_i32_e32 v32, 31, v11
	v_bitop3_b32 v11, v32, v11, s85 bitop3:0x36
	v_ashrrev_i32_e32 v32, 31, v28
	v_or_b32_e32 v32, 0x80000000, v32
	v_bitop3_b32 v28, v32, s86, v28 bitop3:0x48
	v_ashrrev_i32_e32 v32, 31, v12
	v_bitop3_b32 v12, v32, v12, s85 bitop3:0x36
	v_ashrrev_i32_e32 v32, 31, v29
	v_or_b32_e32 v32, 0x80000000, v32
	v_bitop3_b32 v29, v32, s86, v29 bitop3:0x48
	v_ashrrev_i32_e32 v32, 31, v13
	v_bitop3_b32 v13, v32, v13, s85 bitop3:0x36
	v_ashrrev_i32_e32 v32, 31, v30
	v_or_b32_e32 v32, 0x80000000, v32
	v_bitop3_b32 v30, v32, s86, v30 bitop3:0x48
	v_ashrrev_i32_e32 v32, 31, v14
	v_bitop3_b32 v14, v32, v14, s85 bitop3:0x36
	v_ashrrev_i32_e32 v32, 31, v31
	v_or_b32_e32 v32, 0x80000000, v32
	v_bitop3_b32 v31, v32, s86, v31 bitop3:0x48
	v_ashrrev_i32_e32 v32, 31, v15
	v_bitop3_b32 v15, v32, v15, s85 bitop3:0x36
	v_and_or_b32 v0, v0, s86, v72
	v_and_or_b32 v1, v1, s86, v73
	v_and_or_b32 v2, v2, s86, v74
	v_and_or_b32 v3, v3, s86, v75
	v_and_or_b32 v4, v4, s86, v76
	v_and_or_b32 v5, v5, s86, v77
	v_and_or_b32 v6, v6, s86, v78
	v_and_or_b32 v7, v7, s86, v79
	v_and_or_b32 v8, v8, s86, v80
	v_and_or_b32 v9, v9, s86, v81
	v_and_or_b32 v10, v10, s86, v82
	v_and_or_b32 v11, v11, s86, v83
	v_and_or_b32 v12, v12, s86, v84
	v_and_or_b32 v13, v13, s86, v85
	v_and_or_b32 v14, v14, s86, v86
	v_and_or_b32 v15, v15, s86, v87
	v_or3_b32 v16, v70, v16, v72
	v_or3_b32 v0, v0, v70, 32
	v_or3_b32 v17, v70, v17, v73
	v_or3_b32 v1, v1, v70, 32
	v_or3_b32 v18, v70, v18, v74
	v_or3_b32 v2, v2, v70, 32
	v_or3_b32 v19, v70, v19, v75
	v_or3_b32 v3, v3, v70, 32
	v_or3_b32 v20, v70, v20, v76
	v_or3_b32 v4, v4, v70, 32
	v_or3_b32 v21, v70, v21, v77
	v_or3_b32 v5, v5, v70, 32
	v_or3_b32 v22, v70, v22, v78
	v_or3_b32 v6, v6, v70, 32
	v_or3_b32 v23, v70, v23, v79
	v_or3_b32 v7, v7, v70, 32
	v_or3_b32 v24, v70, v24, v80
	v_or3_b32 v8, v8, v70, 32
	v_or3_b32 v25, v70, v25, v81
	v_or3_b32 v9, v9, v70, 32
	v_or3_b32 v26, v70, v26, v82
	v_or3_b32 v10, v10, v70, 32
	v_or3_b32 v27, v70, v27, v83
	v_or3_b32 v11, v11, v70, 32
	v_or3_b32 v28, v70, v28, v84
	v_or3_b32 v12, v12, v70, 32
	v_or3_b32 v29, v70, v29, v85
	v_or3_b32 v13, v13, v70, 32
	v_or3_b32 v30, v70, v30, v86
	v_or3_b32 v14, v14, v70, 32
	v_or3_b32 v31, v70, v31, v87
	v_or3_b32 v15, v15, v70, 32
	v_max_u32_e32 v32, v16, v29
	v_min_u32_e32 v16, v16, v29
	v_max_u32_e32 v29, v17, v28
	v_min_u32_e32 v17, v17, v28
	v_max_u32_e32 v28, v18, v31
	v_min_u32_e32 v18, v18, v31
	v_max_u32_e32 v31, v19, v30
	v_min_u32_e32 v19, v19, v30
	v_max_u32_e32 v30, v20, v24
	v_min_u32_e32 v20, v20, v24
	v_max_u32_e32 v24, v21, v22
	v_min_u32_e32 v21, v21, v22
	v_max_u32_e32 v22, v23, v27
	v_min_u32_e32 v23, v23, v27
	v_max_u32_e32 v27, v25, v26
	v_min_u32_e32 v25, v25, v26
	v_max_u32_e32 v40, v0, v13
	v_min_u32_e32 v0, v0, v13
	v_max_u32_e32 v13, v1, v12
	v_min_u32_e32 v1, v1, v12
	v_max_u32_e32 v12, v2, v15
	v_min_u32_e32 v2, v2, v15
	v_max_u32_e32 v15, v3, v14
	v_min_u32_e32 v3, v3, v14
	v_max_u32_e32 v14, v4, v8
	v_min_u32_e32 v4, v4, v8
	v_max_u32_e32 v8, v5, v6
	v_min_u32_e32 v5, v5, v6
	v_max_u32_e32 v6, v7, v11
	v_min_u32_e32 v7, v7, v11
	v_max_u32_e32 v11, v9, v10
	v_min_u32_e32 v9, v9, v10
	v_max_u32_e32 v26, v32, v24
	v_min_u32_e32 v24, v32, v24
	v_max_u32_e32 v32, v29, v22
	v_min_u32_e32 v22, v29, v22
	v_max_u32_e32 v29, v28, v27
	v_min_u32_e32 v27, v28, v27
	v_max_u32_e32 v28, v31, v30
	v_min_u32_e32 v30, v31, v30
	v_max_u32_e32 v31, v21, v16
	v_min_u32_e32 v16, v21, v16
	v_max_u32_e32 v21, v20, v19
	v_min_u32_e32 v19, v20, v19
	v_max_u32_e32 v20, v25, v18
	v_min_u32_e32 v18, v25, v18
	v_max_u32_e32 v25, v23, v17
	v_min_u32_e32 v17, v23, v17
	v_max_u32_e32 v10, v40, v8
	v_min_u32_e32 v8, v40, v8
	v_max_u32_e32 v40, v13, v6
	v_min_u32_e32 v6, v13, v6
	v_max_u32_e32 v13, v12, v11
	v_min_u32_e32 v11, v12, v11
	v_max_u32_e32 v12, v15, v14
	v_min_u32_e32 v14, v15, v14
	v_max_u32_e32 v15, v5, v0
	v_min_u32_e32 v0, v5, v0
	v_max_u32_e32 v5, v4, v3
	v_min_u32_e32 v3, v4, v3
	v_max_u32_e32 v4, v9, v2
	v_min_u32_e32 v2, v9, v2
	v_max_u32_e32 v9, v7, v1
	v_min_u32_e32 v1, v7, v1
	v_max_u32_e32 v23, v26, v32
	v_min_u32_e32 v26, v26, v32
	v_max_u32_e32 v32, v29, v28
	v_min_u32_e32 v28, v29, v28
	v_max_u32_e32 v29, v30, v24
	v_min_u32_e32 v24, v30, v24
	v_max_u32_e32 v30, v31, v21
	v_min_u32_e32 v21, v31, v21
	v_max_u32_e32 v31, v22, v27
	v_min_u32_e32 v22, v22, v27
	v_max_u32_e32 v27, v20, v25
	v_min_u32_e32 v20, v20, v25
	v_max_u32_e32 v25, v17, v16
	v_min_u32_e32 v16, v17, v16
	v_max_u32_e32 v17, v19, v18
	v_min_u32_e32 v18, v19, v18
	v_max_u32_e32 v7, v10, v40
	v_min_u32_e32 v10, v10, v40
	v_max_u32_e32 v40, v13, v12
	v_min_u32_e32 v12, v13, v12
	v_max_u32_e32 v13, v14, v8
	v_min_u32_e32 v8, v14, v8
	v_max_u32_e32 v14, v15, v5
	v_min_u32_e32 v5, v15, v5
	v_max_u32_e32 v15, v6, v11
	v_min_u32_e32 v6, v6, v11
	v_max_u32_e32 v11, v4, v9
	v_min_u32_e32 v4, v4, v9
	v_max_u32_e32 v9, v1, v0
	v_min_u32_e32 v0, v1, v0
	v_max_u32_e32 v1, v3, v2
	v_min_u32_e32 v2, v3, v2
	v_min_u32_e32 v19, v23, v32
	v_max_u32_e32 v33, v26, v28
	v_min_u32_e32 v26, v26, v28
	v_max_u32_e32 v28, v29, v27
	v_min_u32_e32 v27, v29, v27
	v_max_u32_e32 v29, v24, v20
	v_min_u32_e32 v20, v24, v20
	v_max_u32_e32 v24, v30, v31
	v_min_u32_e32 v30, v30, v31
	v_max_u32_e32 v31, v21, v22
	v_min_u32_e32 v21, v21, v22
	v_max_u32_e32 v22, v25, v17
	v_min_u32_e32 v17, v25, v17
	v_max_u32_e32 v25, v16, v18
	v_min_u32_e32 v3, v7, v40
	v_max_u32_e32 v41, v10, v12
	v_min_u32_e32 v10, v10, v12
	v_max_u32_e32 v12, v13, v11
	v_min_u32_e32 v11, v13, v11
	v_max_u32_e32 v13, v8, v4
	v_min_u32_e32 v4, v8, v4
	v_max_u32_e32 v8, v14, v15
	v_min_u32_e32 v14, v14, v15
	v_max_u32_e32 v15, v5, v6
	v_min_u32_e32 v5, v5, v6
	v_max_u32_e32 v6, v9, v1
	v_min_u32_e32 v1, v9, v1
	v_max_u32_e32 v9, v0, v2
	v_min_u32_e32 v16, v16, v18
	v_max_u32_e32 v18, v33, v19
	v_min_u32_e32 v19, v33, v19
	v_max_u32_e32 v33, v26, v22
	v_min_u32_e32 v22, v26, v22
	v_max_u32_e32 v26, v28, v24
	v_min_u32_e32 v24, v28, v24
	v_max_u32_e32 v28, v29, v30
	v_min_u32_e32 v29, v29, v30
	v_max_u32_e32 v30, v31, v27
	v_min_u32_e32 v27, v31, v27
	v_max_u32_e32 v31, v21, v20
	v_min_u32_e32 v20, v21, v20
	v_max_u32_e32 v21, v25, v17
	v_min_u32_e32 v0, v0, v2
	v_max_u32_e32 v2, v41, v3
	v_min_u32_e32 v3, v41, v3
	v_max_u32_e32 v41, v10, v6
	v_min_u32_e32 v6, v10, v6
	v_max_u32_e32 v10, v12, v8
	v_min_u32_e32 v8, v12, v8
	v_max_u32_e32 v12, v13, v14
	v_min_u32_e32 v13, v13, v14
	v_max_u32_e32 v14, v15, v11
	v_min_u32_e32 v11, v15, v11
	v_max_u32_e32 v15, v5, v4
	v_min_u32_e32 v4, v5, v4
	v_max_u32_e32 v5, v9, v1
	v_min_u32_e32 v17, v25, v17
	v_max_u32_e32 v34, v19, v24
	v_min_u32_e32 v19, v19, v24
	v_max_u32_e32 v24, v28, v30
	v_min_u32_e32 v28, v28, v30
	v_max_u32_e32 v30, v29, v27
	v_min_u32_e32 v27, v29, v27
	v_max_u32_e32 v29, v31, v21
	v_min_u32_e32 v1, v9, v1
	v_max_u32_e32 v42, v3, v8
	v_min_u32_e32 v3, v3, v8
	v_max_u32_e32 v8, v12, v14
	v_min_u32_e32 v12, v12, v14
	v_max_u32_e32 v14, v13, v11
	v_min_u32_e32 v11, v13, v11
	v_max_u32_e32 v13, v15, v5
	v_min_u32_e32 v21, v31, v21
	v_max_u32_e32 v31, v20, v17
	v_max_u32_e32 v35, v33, v19
	v_min_u32_e32 v19, v33, v19
	v_max_u32_e32 v33, v29, v22
	v_min_u32_e32 v22, v29, v22
	v_min_u32_e32 v5, v15, v5
	v_max_u32_e32 v15, v4, v1
	v_max_u32_e32 v43, v41, v3
	v_min_u32_e32 v3, v41, v3
	v_max_u32_e32 v41, v13, v6
	v_min_u32_e32 v6, v13, v6
	v_min_u32_e32 v25, v18, v26
	v_max_u32_e32 v29, v31, v21
	v_min_u32_e32 v21, v31, v21
	v_max_u32_e32 v31, v35, v24
	v_min_u32_e32 v24, v35, v24
	v_max_u32_e32 v35, v19, v28
	v_min_u32_e32 v19, v19, v28
	v_max_u32_e32 v28, v30, v33
	v_min_u32_e32 v30, v30, v33
	v_max_u32_e32 v33, v27, v22
	v_min_u32_e32 v9, v2, v10
	v_max_u32_e32 v13, v15, v5
	v_min_u32_e32 v5, v15, v5
	v_max_u32_e32 v15, v43, v8
	v_min_u32_e32 v8, v43, v8
	v_max_u32_e32 v43, v3, v12
	v_min_u32_e32 v3, v3, v12
	v_max_u32_e32 v12, v14, v41
	v_min_u32_e32 v14, v14, v41
	v_max_u32_e32 v41, v11, v6
	v_min_u32_e32 v17, v20, v17
	v_min_u32_e32 v20, v34, v25
	v_min_u32_e32 v22, v27, v22
	v_min_u32_e32 v36, v24, v35
	v_max_u32_e32 v37, v28, v19
	v_min_u32_e32 v19, v28, v19
	v_max_u32_e32 v28, v30, v33
	v_min_u32_e32 v1, v4, v1
	v_min_u32_e32 v4, v42, v9
	v_min_u32_e32 v6, v11, v6
	v_min_u32_e32 v44, v8, v43
	v_max_u32_e32 v45, v12, v3
	v_min_u32_e32 v3, v12, v3
	v_max_u32_e32 v12, v14, v41
	v_min_u32_e32 v27, v31, v20
	v_min_u32_e32 v30, v30, v33
	v_min_u32_e32 v33, v29, v22
	v_min_u32_e32 v38, v36, v37
	v_min_u32_e32 v39, v19, v28
	v_min_u32_e32 v11, v15, v4
	v_min_u32_e32 v14, v14, v41
	v_min_u32_e32 v41, v13, v6
	v_min_u32_e32 v46, v44, v45
	v_min_u32_e32 v47, v3, v12
	v_max3_u32 v0, v23, v32, v0
	v_max3_u32 v1, v18, v26, v1
	v_max3_u32 v5, v34, v25, v5
	v_max3_u32 v18, v31, v20, v41
	v_max3_u32 v6, v27, v13, v6
	v_max3_u32 v13, v24, v35, v14
	v_max3_u32 v14, v36, v37, v47
	v_max3_u32 v3, v38, v3, v12
	v_max3_u32 v12, v19, v28, v46
	v_max3_u32 v19, v39, v44, v45
	v_max3_u32 v8, v30, v8, v43
	v_max3_u32 v11, v29, v22, v11
	v_max3_u32 v4, v33, v15, v4
	v_max3_u32 v9, v21, v42, v9
	v_max3_u32 v2, v17, v2, v10
	v_max3_u32 v7, v16, v7, v40
	v_max_u32_e32 v10, v0, v12
	v_min_u32_e32 v0, v0, v12
	v_max_u32_e32 v12, v1, v19
	v_max_u32_e32 v15, v5, v8
	v_min_u32_e32 v5, v5, v8
	v_max_u32_e32 v8, v18, v11
	v_max_u32_e32 v16, v6, v4
	v_min_u32_e32 v4, v6, v4
	v_max_u32_e32 v6, v13, v9
	v_min_u32_e32 v9, v13, v9
	v_max_u32_e32 v13, v14, v2
	v_min_u32_e32 v2, v14, v2
	v_max_u32_e32 v14, v3, v7
	v_min_u32_e32 v1, v1, v19
	v_min_u32_e32 v11, v18, v11
	v_min_u32_e32 v3, v3, v7
	v_max_u32_e32 v7, v10, v16
	v_min_u32_e32 v10, v10, v16
	v_max_u32_e32 v16, v12, v6
	v_min_u32_e32 v6, v12, v6
	v_max_u32_e32 v12, v15, v13
	v_min_u32_e32 v13, v15, v13
	v_max_u32_e32 v15, v8, v14
	v_min_u32_e32 v8, v8, v14
	v_max_u32_e32 v14, v0, v4
	v_min_u32_e32 v0, v0, v4
	v_max_u32_e32 v4, v1, v9
	v_min_u32_e32 v1, v1, v9
	v_max_u32_e32 v9, v5, v2
	v_min_u32_e32 v2, v5, v2
	v_max_u32_e32 v5, v11, v3
	v_min_u32_e32 v3, v11, v3
	v_max_u32_e32 v11, v7, v12
	v_min_u32_e32 v7, v7, v12
	v_max_u32_e32 v12, v16, v15
	v_min_u32_e32 v15, v16, v15
	v_max_u32_e32 v16, v10, v13
	v_min_u32_e32 v10, v10, v13
	v_max_u32_e32 v13, v6, v8
	v_max_u32_e32 v17, v14, v9
	v_min_u32_e32 v14, v14, v9
	v_max_u32_e32 v9, v4, v5
	v_min_u32_e32 v18, v4, v5
	v_max_u32_e32 v4, v16, v13
	v_min_u32_e32 v5, v16, v13
	v_or3_b32 v16, v68, v48, v69
	v_lshlrev_b32_e32 v16, 6, v16
	v_min_u32_e32 v8, v6, v8
	v_max_u32_e32 v19, v0, v2
	v_min_u32_e32 v20, v0, v2
	v_max_u32_e32 v21, v1, v3
	v_min_u32_e32 v22, v1, v3
	v_max_u32_e32 v0, v11, v12
	v_min_u32_e32 v1, v11, v12
	v_max_u32_e32 v2, v7, v15
	v_min_u32_e32 v3, v7, v15
	v_mad_i32_i24 v16, v67, s75, v16
	v_max_u32_e32 v6, v10, v8
	v_min_u32_e32 v7, v10, v8
	v_max_u32_e32 v8, v17, v9
	v_min_u32_e32 v9, v17, v9
	v_max_u32_e32 v10, v14, v18
	v_min_u32_e32 v11, v14, v18
	v_max_u32_e32 v12, v19, v21
	v_min_u32_e32 v13, v19, v21
	v_max_u32_e32 v14, v20, v22
	v_min_u32_e32 v15, v20, v22
	v_bfe_u32 v240, v16, 8, 4
	v_lshlrev_b32_e32 v240, 4, v240
	v_xor_b32_e32 v240, v16, v240
	ds_write_b128 v240, v[0:3] offset:8192
	v_xor_b32_e32 v241, 16, v240
	ds_write_b128 v241, v[4:7] offset:8192
	v_xor_b32_e32 v241, 32, v240
	ds_write_b128 v241, v[8:11] offset:8192
	v_xor_b32_e32 v241, 48, v240
	ds_write_b128 v241, v[12:15] offset:8192
	s_waitcnt lgkmcnt(0)
	s_barrier
	s_and_saveexec_b64 s[60:61], vcc
	s_cbranch_execz .LBB0_856
	v_lshl_add_u32 v60, v65, 8, v66
	v_bfe_u32 v240, v60, 8, 4
	v_lshlrev_b32_e32 v240, 4, v240
	v_xor_b32_e32 v240, v60, v240
	ds_read_b128 v[0:3], v240
	v_xor_b32_e32 v241, 16, v240
	ds_read_b128 v[4:7], v241
	v_xor_b32_e32 v241, 32, v240
	ds_read_b128 v[8:11], v241
	v_xor_b32_e32 v241, 48, v240
	ds_read_b128 v[12:15], v241
	v_xor_b32_e32 v241, 64, v240
	ds_read_b128 v[16:19], v241
	v_xor_b32_e32 v241, 0x50, v240
	ds_read_b128 v[20:23], v241
	v_xor_b32_e32 v241, 0x80, v240
	ds_read_b128 v[24:27], v241
	v_xor_b32_e32 v241, 0x90, v240
	ds_read_b128 v[28:31], v241
	v_xor_b32_e32 v241, 0xc0, v240
	ds_read_b128 v[32:35], v241
	v_xor_b32_e32 v241, 0xd0, v240
	ds_read_b128 v[36:39], v241
	v_xor_b32_e32 v241, 0x60, v240
	ds_read_b128 v[40:43], v241
	v_xor_b32_e32 v241, 0x70, v240
	ds_read_b128 v[44:47], v241
	v_xor_b32_e32 v241, 0xa0, v240
	ds_read_b128 v[48:51], v241
	v_xor_b32_e32 v241, 0xb0, v240
	ds_read_b128 v[52:55], v241
	v_xor_b32_e32 v241, 0xe0, v240
	ds_read_b128 v[56:59], v241
	v_xor_b32_e32 v241, 0xf0, v240
	ds_read_b128 v[60:63], v241
	s_waitcnt lgkmcnt(4)
	v_max_u32_e32 v0, v0, v47
	v_max_u32_e32 v1, v1, v46
	v_max_u32_e32 v2, v2, v45
	v_max_u32_e32 v3, v3, v44
	v_max_u32_e32 v4, v4, v43
	v_max_u32_e32 v5, v5, v42
	v_max_u32_e32 v6, v6, v41
	v_max_u32_e32 v7, v7, v40
	v_max_u32_e32 v8, v8, v23
	v_max_u32_e32 v9, v9, v22
	v_max_u32_e32 v10, v10, v21
	v_max_u32_e32 v11, v11, v20
	v_max_u32_e32 v12, v12, v19
	v_max_u32_e32 v13, v13, v18
	v_max_u32_e32 v14, v14, v17
	v_max_u32_e32 v15, v15, v16
	s_waitcnt lgkmcnt(0)
	v_max_u32_e32 v24, v24, v63
	v_max_u32_e32 v25, v25, v62
	v_max_u32_e32 v26, v26, v61
	v_max_u32_e32 v27, v27, v60
	v_max_u32_e32 v28, v28, v59
	v_max_u32_e32 v29, v29, v58
	v_max_u32_e32 v30, v30, v57
	v_max_u32_e32 v31, v31, v56
	v_max_u32_e32 v39, v48, v39
	v_max_u32_e32 v38, v49, v38
	v_max_u32_e32 v37, v50, v37
	v_max_u32_e32 v36, v51, v36
	v_max_u32_e32 v35, v52, v35
	v_max_u32_e32 v34, v53, v34
	v_max_u32_e32 v33, v54, v33
	v_max_u32_e32 v32, v55, v32
	v_max_u32_e32 v16, v0, v8
	v_min_u32_e32 v0, v0, v8
	v_max_u32_e32 v8, v1, v9
	v_min_u32_e32 v1, v1, v9
	v_max_u32_e32 v9, v2, v10
	v_min_u32_e32 v2, v2, v10
	v_max_u32_e32 v10, v3, v11
	v_min_u32_e32 v3, v3, v11
	v_max_u32_e32 v11, v4, v12
	v_min_u32_e32 v4, v4, v12
	v_max_u32_e32 v12, v5, v13
	v_min_u32_e32 v5, v5, v13
	v_max_u32_e32 v13, v6, v14
	v_min_u32_e32 v6, v6, v14
	v_max_u32_e32 v14, v7, v15
	v_min_u32_e32 v7, v7, v15
	v_max_u32_e32 v40, v24, v39
	v_min_u32_e32 v24, v24, v39
	v_max_u32_e32 v39, v25, v38
	v_min_u32_e32 v25, v25, v38
	v_max_u32_e32 v38, v26, v37
	v_min_u32_e32 v26, v26, v37
	v_max_u32_e32 v37, v27, v36
	v_min_u32_e32 v27, v27, v36
	v_max_u32_e32 v36, v28, v35
	v_min_u32_e32 v28, v28, v35
	v_max_u32_e32 v35, v29, v34
	v_min_u32_e32 v29, v29, v34
	v_max_u32_e32 v34, v30, v33
	v_min_u32_e32 v30, v30, v33
	v_max_u32_e32 v33, v31, v32
	v_min_u32_e32 v31, v31, v32
	v_max_u32_e32 v15, v16, v11
	v_min_u32_e32 v11, v16, v11
	v_max_u32_e32 v16, v8, v12
	v_min_u32_e32 v8, v8, v12
	v_max_u32_e32 v12, v9, v13
	v_min_u32_e32 v9, v9, v13
	v_max_u32_e32 v13, v10, v14
	v_min_u32_e32 v10, v10, v14
	v_max_u32_e32 v14, v0, v4
	v_min_u32_e32 v0, v0, v4
	v_max_u32_e32 v4, v1, v5
	v_min_u32_e32 v1, v1, v5
	v_max_u32_e32 v5, v2, v6
	v_min_u32_e32 v2, v2, v6
	v_max_u32_e32 v6, v3, v7
	v_min_u32_e32 v3, v3, v7
	v_max_u32_e32 v32, v40, v36
	v_min_u32_e32 v36, v40, v36
	v_max_u32_e32 v40, v39, v35
	v_min_u32_e32 v35, v39, v35
	v_max_u32_e32 v39, v38, v34
	v_min_u32_e32 v34, v38, v34
	v_max_u32_e32 v38, v37, v33
	v_min_u32_e32 v33, v37, v33
	v_max_u32_e32 v37, v24, v28
	v_min_u32_e32 v24, v24, v28
	v_max_u32_e32 v28, v25, v29
	v_min_u32_e32 v25, v25, v29
	v_max_u32_e32 v29, v26, v30
	v_min_u32_e32 v26, v26, v30
	v_max_u32_e32 v30, v27, v31
	v_min_u32_e32 v27, v27, v31
	v_max_u32_e32 v7, v15, v12
	v_min_u32_e32 v12, v15, v12
	v_max_u32_e32 v15, v16, v13
	v_min_u32_e32 v13, v16, v13
	v_max_u32_e32 v16, v11, v9
	v_min_u32_e32 v9, v11, v9
	v_max_u32_e32 v11, v8, v10
	v_min_u32_e32 v8, v8, v10
	v_max_u32_e32 v10, v14, v5
	v_min_u32_e32 v5, v14, v5
	v_max_u32_e32 v14, v4, v6
	v_min_u32_e32 v4, v4, v6
	v_max_u32_e32 v6, v0, v2
	v_min_u32_e32 v0, v0, v2
	v_max_u32_e32 v2, v1, v3
	v_min_u32_e32 v1, v1, v3
	v_max_u32_e32 v31, v32, v39
	v_min_u32_e32 v32, v32, v39
	v_max_u32_e32 v39, v40, v38
	v_min_u32_e32 v38, v40, v38
	v_max_u32_e32 v40, v36, v34
	v_min_u32_e32 v34, v36, v34
	v_max_u32_e32 v36, v35, v33
	v_min_u32_e32 v33, v35, v33
	v_max_u32_e32 v35, v37, v29
	v_min_u32_e32 v29, v37, v29
	v_max_u32_e32 v37, v28, v30
	v_min_u32_e32 v28, v28, v30
	v_max_u32_e32 v30, v24, v26
	v_min_u32_e32 v24, v24, v26
	v_max_u32_e32 v26, v25, v27
	v_min_u32_e32 v25, v25, v27
	v_min_u32_e32 v3, v7, v15
	v_min_u32_e32 v17, v12, v13
	v_min_u32_e32 v18, v16, v11
	v_min_u32_e32 v19, v9, v8
	v_min_u32_e32 v20, v10, v14
	v_min_u32_e32 v21, v5, v4
	v_min_u32_e32 v22, v6, v2
	v_min_u32_e32 v23, v0, v1
	v_min_u32_e32 v27, v31, v39
	v_min_u32_e32 v41, v32, v38
	v_min_u32_e32 v42, v40, v36
	v_min_u32_e32 v43, v34, v33
	v_min_u32_e32 v44, v35, v37
	v_min_u32_e32 v45, v29, v28
	v_min_u32_e32 v46, v30, v26
	v_min_u32_e32 v47, v24, v25
	v_max3_u32 v7, v7, v15, v47
	v_max3_u32 v3, v3, v24, v25
	v_max3_u32 v12, v12, v13, v46
	v_max3_u32 v13, v17, v30, v26
	v_max3_u32 v11, v16, v11, v45
	v_max3_u32 v15, v18, v29, v28
	v_max3_u32 v8, v9, v8, v44
	v_max3_u32 v9, v19, v35, v37
	v_max3_u32 v10, v10, v14, v43
	v_max3_u32 v14, v20, v34, v33
	v_max3_u32 v4, v5, v4, v42
	v_max3_u32 v5, v21, v40, v36
	v_max3_u32 v2, v6, v2, v41
	v_max3_u32 v6, v22, v32, v38
	v_max3_u32 v0, v0, v1, v27
	v_max3_u32 v1, v23, v31, v39
	v_max_u32_e32 v16, v7, v10
	v_min_u32_e32 v7, v7, v10
	v_max_u32_e32 v10, v3, v14
	v_min_u32_e32 v3, v3, v14
	v_max_u32_e32 v14, v12, v4
	v_min_u32_e32 v4, v12, v4
	v_max_u32_e32 v12, v13, v5
	v_min_u32_e32 v5, v13, v5
	v_max_u32_e32 v13, v11, v2
	v_min_u32_e32 v2, v11, v2
	v_max_u32_e32 v11, v15, v6
	v_min_u32_e32 v6, v15, v6
	v_max_u32_e32 v15, v8, v0
	v_min_u32_e32 v0, v8, v0
	v_max_u32_e32 v8, v9, v1
	v_min_u32_e32 v1, v9, v1
	v_max_u32_e32 v9, v16, v13
	v_min_u32_e32 v13, v16, v13
	v_max_u32_e32 v16, v10, v11
	v_min_u32_e32 v10, v10, v11
	v_max_u32_e32 v11, v14, v15
	v_min_u32_e32 v14, v14, v15
	v_max_u32_e32 v15, v12, v8
	v_min_u32_e32 v8, v12, v8
	v_max_u32_e32 v12, v7, v2
	v_min_u32_e32 v2, v7, v2
	v_max_u32_e32 v7, v3, v6
	v_min_u32_e32 v3, v3, v6
	v_max_u32_e32 v6, v4, v0
	v_min_u32_e32 v0, v4, v0
	v_max_u32_e32 v4, v5, v1
	v_min_u32_e32 v1, v5, v1
	v_max_u32_e32 v5, v9, v11
	v_min_u32_e32 v9, v9, v11
	v_max_u32_e32 v11, v16, v15
	v_min_u32_e32 v15, v16, v15
	v_max_u32_e32 v16, v13, v14
	v_min_u32_e32 v13, v13, v14
	v_max_u32_e32 v14, v10, v8
	v_min_u32_e32 v8, v10, v8
	v_max_u32_e32 v10, v12, v6
	v_max_u32_e32 v17, v7, v4
	v_min_u32_e32 v18, v7, v4
	v_max_u32_e32 v19, v2, v0
	v_min_u32_e32 v20, v2, v0
	v_max_u32_e32 v21, v3, v1
	v_min_u32_e32 v22, v3, v1
	v_max_u32_e32 v0, v5, v11
	v_min_u32_e32 v1, v5, v11
	v_max_u32_e32 v4, v16, v14
	v_min_u32_e32 v5, v16, v14
	v_or_b32_e32 v16, s58, v65
	v_min_u32_e32 v12, v12, v6
	v_max_u32_e32 v2, v9, v15
	v_min_u32_e32 v3, v9, v15
	v_max_u32_e32 v6, v13, v8
	v_min_u32_e32 v7, v13, v8
	v_max_u32_e32 v8, v10, v17
	v_min_u32_e32 v9, v10, v17
	v_ashrrev_i32_e32 v17, 31, v16
	v_max_u32_e32 v10, v12, v18
	v_min_u32_e32 v11, v12, v18
	v_lshlrev_b64 v[16:17], 10, v[16:17]
	v_lshlrev_b32_e32 v18, 4, v64
	v_max_u32_e32 v12, v19, v21
	v_min_u32_e32 v13, v19, v21
	v_lshl_add_u64 v[16:17], s[12:13], 0, v[16:17]
	v_ashrrev_i32_e32 v19, 31, v18
	v_lshl_add_u64 v[16:17], v[18:19], 2, v[16:17]
	v_max_u32_e32 v14, v20, v22
	v_min_u32_e32 v15, v20, v22
	v_and_b32_e32 v238, 3, v65
	v_lshl_add_u32 v239, v65, 8, v66
	v_lshl_add_u32 v239, v238, 6, v239
	ds_write_b128 v239, v[0:3]
	ds_write_b128 v239, v[4:7] offset:16
	ds_write_b128 v239, v[8:11] offset:32
	ds_write_b128 v239, v[12:15] offset:48
	v_bfe_u32 v242, v65, 2, 4
	v_and_or_b32 v242, v65, 64, v242
	v_and_b32_e32 v243, 3, v242
	v_lshlrev_b32_e32 v243, 6, v243
	v_lshl_add_u32 v243, v238, 4, v243
	v_lshl_add_u32 v243, v242, 8, v243
	v_add_u32_e32 v243, v66, v243
	ds_read_b128 v[20:23], v243
	ds_read_b128 v[24:27], v243 offset:4096
	ds_read_b128 v[28:31], v243 offset:8192
	ds_read_b128 v[32:35], v243 offset:12288
	v_or_b32_e32 v244, s58, v242
	v_ashrrev_i32_e32 v245, 31, v244
	v_lshlrev_b64 v[244:245], 10, v[244:245]
	v_lshl_add_u64 v[244:245], s[12:13], 0, v[244:245]
	v_lshl_add_u64 v[244:245], v[18:19], 2, v[244:245]
	v_lshlrev_b32_e32 v246, 4, v238
	v_mov_b32_e32 v247, 0
	v_lshl_add_u64 v[244:245], v[244:245], 0, v[246:247]
	v_mov_b32_e32 v246, 0x4000
	s_waitcnt lgkmcnt(3)
	global_store_dwordx4 v[244:245], v[20:23], off
	v_lshl_add_u64 v[244:245], v[244:245], 0, v[246:247]
	s_waitcnt lgkmcnt(2)
	global_store_dwordx4 v[244:245], v[24:27], off
	v_lshl_add_u64 v[244:245], v[244:245], 0, v[246:247]
	s_waitcnt lgkmcnt(1)
	global_store_dwordx4 v[244:245], v[28:31], off
	v_lshl_add_u64 v[244:245], v[244:245], 0, v[246:247]
	s_waitcnt lgkmcnt(0)
	global_store_dwordx4 v[244:245], v[32:35], off
	s_branch .LBB0_856
